# weight conversion: XOR-swizzled LDS transpose tile (8-way write conflicts -> 2-way)
# baseline (speedup 1.0000x reference)
; #define LAS __attribute__((address_space(3)))
; __device__ __forceinline__ int fresh_tid() { int t = threadIdx.x; asm volatile("" : "+v"(t)); return t; }
; __device__ __forceinline__ void convert_wt(LAS unsigned char* lds, const float* __restrict__ W, bf16_t* __restrict__ Wt, int K, int N, int mode) {
;     LAS bf16_t* T = (LAS bf16_t*)lds;
;     const int tid = fresh_tid();
;     const int nsn = N / 512, nsuper = (K / 64) * nsn;
;     const int kk0 = tid >> 4, c4 = (tid & 15) * 4;
;     f32x4 v[16];
;     ...
;     int st = blockIdx.x;
;     if (st < nsuper) CW_LOAD(st);
.LBB0_11:
	v_readlane_b32 s0, v254, 58
	v_readlane_b32 s1, v254, 59
	s_mov_b32 s5, s1
	v_readlane_b32 s0, v250, 25
	v_readlane_b32 s1, v250, 26
	v_writelane_b32 v251, s4, 38
	v_mov_b32_e32 v66, v230
	s_andn2_b64 vcc, exec, s[0:1]
	v_writelane_b32 v251, s5, 39
	s_cbranch_vccnz .LBB0_17
	s_mul_i32 s0, s4, 0x5000000
	v_readlane_b32 s4, v250, 4
	v_readlane_b32 s10, v250, 10
	v_lshlrev_b32_e32 v0, 2, v66
	v_readlane_b32 s11, v250, 11
	s_add_u32 s0, s10, s0
	v_and_b32_e32 v67, 60, v0
	s_addc_u32 s1, s11, 0
	v_lshlrev_b32_e32 v0, 2, v67
	v_mov_b32_e32 v1, v192
	v_lshl_add_u64 v[64:65], s[0:1], 0, v[0:1]
	v_readlane_b32 s0, v250, 28
	v_ashrrev_i32_e32 v68, 4, v66
	v_readlane_b32 s4, v250, 27
	v_readlane_b32 s1, v250, 29
	v_lshlrev_b32_e32 v70, 1, v68
	v_add_u32_e32 v2, s4, v68
	v_lshl_add_u64 v[0:1], s[0:1], 2, v[64:65]
	v_mad_i64_i32 v[52:53], s[0:1], v2, s63, v[0:1]
	v_add_u32_e32 v2, 32, v2
	v_mad_i64_i32 v[60:61], s[0:1], v2, s63, v[0:1]
	global_load_dwordx4 v[0:3], v[52:53], off
	global_load_dwordx4 v[4:7], v[52:53], off offset:256
	global_load_dwordx4 v[8:11], v[60:61], off
	global_load_dwordx4 v[12:15], v[60:61], off offset:256
	global_load_dwordx4 v[16:19], v[52:53], off offset:512
	global_load_dwordx4 v[20:23], v[52:53], off offset:768
	global_load_dwordx4 v[24:27], v[60:61], off offset:512
	global_load_dwordx4 v[28:31], v[60:61], off offset:768
	global_load_dwordx4 v[32:35], v[52:53], off offset:1024
	global_load_dwordx4 v[36:39], v[52:53], off offset:1280
	global_load_dwordx4 v[40:43], v[60:61], off offset:1024
	global_load_dwordx4 v[44:47], v[60:61], off offset:1280
	global_load_dwordx4 v[48:51], v[52:53], off offset:1536
	s_nop 0
	global_load_dwordx4 v[52:55], v[52:53], off offset:1792
	s_nop 0
	global_load_dwordx4 v[56:59], v[60:61], off offset:1536
	s_nop 0
	global_load_dwordx4 v[60:63], v[60:61], off offset:1792
	v_ashrrev_i32_e32 v69, 3, v66
	v_lshlrev_b32_e32 v66, 4, v66
	v_mul_u32_u24_e32 v67, 0x90, v67
	v_readlane_b32 s5, v250, 5
	v_readlane_b32 s6, v250, 6
	v_mul_lo_u32 v71, v69, s64
	v_add3_u32 v70, 0, v70, v67
	v_and_b32_e32 v66, 0x70, v66
	v_mov_b32_e32 v67, v192
	s_lshl_b32 s4, s80, 9
	v_add3_u32 v71, 0, v71, v66
	v_lshl_add_u64 v[66:67], s[78:79], 0, v[66:67]
	s_mov_b32 s5, s4
	s_mov_b32 s6, s75
	v_readlane_b32 s7, v250, 7
	v_readlane_b32 s8, v250, 8
	v_readlane_b32 s9, v250, 9
	v_readlane_b32 s12, v250, 12
	v_readlane_b32 s13, v250, 13
	v_readlane_b32 s14, v250, 14
	v_readlane_b32 s15, v250, 15
	v_readlane_b32 s16, v250, 16
	v_readlane_b32 s17, v250, 17
	v_readlane_b32 s18, v250, 18
	v_readlane_b32 s19, v250, 19
	v_lshrrev_b32_e32 v87, 4, v230
	v_and_b32_e32 v88, 3, v230
	v_lshlrev_b32_e32 v88, 3, v88
	v_xor_b32_e32 v88, v87, v88
	v_sub_u32_e32 v88, v88, v87
	v_bfe_u32 v87, v230, 2, 1
	v_lshlrev_b32_e32 v87, 6, v87
	v_lshl_add_u32 v86, v88, 1, v70
	v_add_u32_e32 v70, v86, v87
	v_sub_u32_e32 v86, v86, v87
	v_and_b32_e32 v87, 7, v230
	v_bfe_u32 v88, v230, 5, 3
	v_xor_b32_e32 v88, v87, v88
	v_sub_u32_e32 v88, v88, v87
	v_lshl_add_u32 v71, v88, 4, v71
	s_branch .LBB0_14

; __device__ __forceinline__ bf16_t f2bf(float f) { unsigned u = __float_as_uint(f); u += 0x7FFFu + ((u >> 16) & 1u); return (bf16_t)(u >> 16); }
; __device__ __forceinline__ void convert_wt(LAS unsigned char* lds, const float* __restrict__ W, bf16_t* __restrict__ Wt, int K, int N, int mode) {
;     ...
; #pragma unroll
;         for (int s_ = 0; s_ < 8; ++s_)
; #pragma unroll
;             for (int i_ = 0; i_ < 2; ++i_)
; #pragma unroll
;                 for (int e = 0; e < 4; ++e) T[s_ * 4608 + (c4 + e) * 72 + kk0 + 32 * i_] = f2bf(v[s_ * 2 + i_][e]);
;         __syncthreads();
.LBB0_14:
	s_waitcnt vmcnt(15)
	v_bfe_u32 v72, v0, 16, 1
	v_add3_u32 v72, v0, v72, s70
	ds_write_b16_d16_hi v70, v72
	v_bfe_u32 v72, v1, 16, 1
	v_add3_u32 v72, v1, v72, s70
	ds_write_b16_d16_hi v70, v72 offset:144
	v_bfe_u32 v72, v2, 16, 1
	v_add3_u32 v72, v2, v72, s70
	ds_write_b16_d16_hi v70, v72 offset:288
	v_bfe_u32 v72, v3, 16, 1
	v_add3_u32 v72, v3, v72, s70
	ds_write_b16_d16_hi v70, v72 offset:432
	s_waitcnt vmcnt(13)
	v_bfe_u32 v72, v8, 16, 1
	v_add3_u32 v72, v8, v72, s70
	ds_write_b16_d16_hi v86, v72 offset:64
	v_bfe_u32 v72, v9, 16, 1
	v_add3_u32 v72, v9, v72, s70
	ds_write_b16_d16_hi v86, v72 offset:208
	v_bfe_u32 v72, v10, 16, 1
	v_add3_u32 v72, v10, v72, s70
	ds_write_b16_d16_hi v86, v72 offset:352
	v_bfe_u32 v72, v11, 16, 1
	v_add3_u32 v72, v11, v72, s70
	ds_write_b16_d16_hi v86, v72 offset:496
	v_bfe_u32 v72, v4, 16, 1
	v_add3_u32 v72, v4, v72, s70
	ds_write_b16_d16_hi v70, v72 offset:9216
	v_bfe_u32 v72, v5, 16, 1
	v_add3_u32 v72, v5, v72, s70
	ds_write_b16_d16_hi v70, v72 offset:9360
	v_bfe_u32 v72, v6, 16, 1
	v_add3_u32 v72, v6, v72, s70
	ds_write_b16_d16_hi v70, v72 offset:9504
	v_bfe_u32 v72, v7, 16, 1
	v_add3_u32 v72, v7, v72, s70
	ds_write_b16_d16_hi v70, v72 offset:9648
	s_waitcnt vmcnt(12)
	v_bfe_u32 v72, v12, 16, 1
	v_add3_u32 v72, v12, v72, s70
	ds_write_b16_d16_hi v86, v72 offset:9280
	v_bfe_u32 v72, v13, 16, 1
	v_add3_u32 v72, v13, v72, s70
	ds_write_b16_d16_hi v86, v72 offset:9424
	v_bfe_u32 v72, v14, 16, 1
	v_add3_u32 v72, v14, v72, s70
	ds_write_b16_d16_hi v86, v72 offset:9568
	v_bfe_u32 v72, v15, 16, 1
	v_add3_u32 v72, v15, v72, s70
	ds_write_b16_d16_hi v86, v72 offset:9712
	s_waitcnt vmcnt(11)
	v_bfe_u32 v72, v16, 16, 1
	v_add3_u32 v72, v16, v72, s70
	ds_write_b16_d16_hi v70, v72 offset:18432
	v_bfe_u32 v72, v17, 16, 1
	v_add3_u32 v72, v17, v72, s70
	ds_write_b16_d16_hi v70, v72 offset:18576
	v_bfe_u32 v72, v18, 16, 1
	v_add3_u32 v72, v18, v72, s70
	ds_write_b16_d16_hi v70, v72 offset:18720
	v_bfe_u32 v72, v19, 16, 1
	v_add3_u32 v72, v19, v72, s70
	ds_write_b16_d16_hi v70, v72 offset:18864
	s_waitcnt vmcnt(9)
	v_bfe_u32 v72, v24, 16, 1
	v_add3_u32 v72, v24, v72, s70
	ds_write_b16_d16_hi v86, v72 offset:18496
	v_bfe_u32 v72, v25, 16, 1
	v_add3_u32 v72, v25, v72, s70
	ds_write_b16_d16_hi v86, v72 offset:18640
	v_bfe_u32 v72, v26, 16, 1
	v_add3_u32 v72, v26, v72, s70
	ds_write_b16_d16_hi v86, v72 offset:18784
	v_bfe_u32 v72, v27, 16, 1
	v_add3_u32 v72, v27, v72, s70
	ds_write_b16_d16_hi v86, v72 offset:18928
	v_bfe_u32 v72, v20, 16, 1
	v_add3_u32 v72, v20, v72, s70
	ds_write_b16_d16_hi v70, v72 offset:27648
	v_bfe_u32 v72, v21, 16, 1
	v_add3_u32 v72, v21, v72, s70
	ds_write_b16_d16_hi v70, v72 offset:27792
	v_bfe_u32 v72, v22, 16, 1
	v_add3_u32 v72, v22, v72, s70
	ds_write_b16_d16_hi v70, v72 offset:27936
	v_bfe_u32 v72, v23, 16, 1
	v_add3_u32 v72, v23, v72, s70
	ds_write_b16_d16_hi v70, v72 offset:28080
	s_waitcnt vmcnt(8)
	v_bfe_u32 v72, v28, 16, 1
	v_add3_u32 v72, v28, v72, s70
	ds_write_b16_d16_hi v86, v72 offset:27712
	v_bfe_u32 v72, v29, 16, 1
	v_add3_u32 v72, v29, v72, s70
	ds_write_b16_d16_hi v86, v72 offset:27856
	v_bfe_u32 v72, v30, 16, 1
	v_add3_u32 v72, v30, v72, s70
	ds_write_b16_d16_hi v86, v72 offset:28000
	v_bfe_u32 v72, v31, 16, 1
	v_add3_u32 v72, v31, v72, s70
	ds_write_b16_d16_hi v86, v72 offset:28144
	s_waitcnt vmcnt(7)
	v_bfe_u32 v72, v32, 16, 1
	v_add3_u32 v72, v32, v72, s70
	ds_write_b16_d16_hi v70, v72 offset:36864
	v_bfe_u32 v72, v33, 16, 1
	v_add3_u32 v72, v33, v72, s70
	ds_write_b16_d16_hi v70, v72 offset:37008
	v_bfe_u32 v72, v34, 16, 1
	v_add3_u32 v72, v34, v72, s70
	ds_write_b16_d16_hi v70, v72 offset:37152
	v_bfe_u32 v72, v35, 16, 1
	v_add3_u32 v72, v35, v72, s70
	ds_write_b16_d16_hi v70, v72 offset:37296
	s_waitcnt vmcnt(5)
	v_bfe_u32 v72, v40, 16, 1
	v_add3_u32 v72, v40, v72, s70
	ds_write_b16_d16_hi v86, v72 offset:36928
	v_bfe_u32 v72, v41, 16, 1
	v_add3_u32 v72, v41, v72, s70
	ds_write_b16_d16_hi v86, v72 offset:37072
	v_bfe_u32 v72, v42, 16, 1
	v_add3_u32 v72, v42, v72, s70
	ds_write_b16_d16_hi v86, v72 offset:37216
	v_bfe_u32 v72, v43, 16, 1
	v_add3_u32 v72, v43, v72, s70
	ds_write_b16_d16_hi v86, v72 offset:37360
	v_bfe_u32 v72, v36, 16, 1
	v_add3_u32 v72, v36, v72, s70
	ds_write_b16_d16_hi v70, v72 offset:46080
	v_bfe_u32 v72, v37, 16, 1
	v_add3_u32 v72, v37, v72, s70
	ds_write_b16_d16_hi v70, v72 offset:46224
	v_bfe_u32 v72, v38, 16, 1
	v_add3_u32 v72, v38, v72, s70
	ds_write_b16_d16_hi v70, v72 offset:46368
	v_bfe_u32 v72, v39, 16, 1
	v_add3_u32 v72, v39, v72, s70
	ds_write_b16_d16_hi v70, v72 offset:46512
	s_waitcnt vmcnt(4)
	v_bfe_u32 v72, v44, 16, 1
	v_add3_u32 v72, v44, v72, s70
	ds_write_b16_d16_hi v86, v72 offset:46144
	v_bfe_u32 v72, v45, 16, 1
	v_add3_u32 v72, v45, v72, s70
	ds_write_b16_d16_hi v86, v72 offset:46288
	v_bfe_u32 v72, v46, 16, 1
	v_add3_u32 v72, v46, v72, s70
	ds_write_b16_d16_hi v86, v72 offset:46432
	v_bfe_u32 v72, v47, 16, 1
	v_add3_u32 v72, v47, v72, s70
	ds_write_b16_d16_hi v86, v72 offset:46576
	s_waitcnt vmcnt(3)
	v_bfe_u32 v72, v48, 16, 1
	v_add3_u32 v72, v48, v72, s70
	ds_write_b16_d16_hi v70, v72 offset:55296
	v_bfe_u32 v72, v49, 16, 1
	v_add3_u32 v72, v49, v72, s70
	ds_write_b16_d16_hi v70, v72 offset:55440
	v_bfe_u32 v72, v50, 16, 1
	v_add3_u32 v72, v50, v72, s70
	ds_write_b16_d16_hi v70, v72 offset:55584
	v_bfe_u32 v72, v51, 16, 1
	v_add3_u32 v72, v51, v72, s70
	ds_write_b16_d16_hi v70, v72 offset:55728
	s_waitcnt vmcnt(1)
	v_bfe_u32 v72, v56, 16, 1
	v_add3_u32 v72, v56, v72, s70
	ds_write_b16_d16_hi v86, v72 offset:55360
	v_bfe_u32 v72, v57, 16, 1
	v_add3_u32 v72, v57, v72, s70
	ds_write_b16_d16_hi v86, v72 offset:55504
	v_bfe_u32 v72, v58, 16, 1
	v_add3_u32 v72, v58, v72, s70
	ds_write_b16_d16_hi v86, v72 offset:55648
	v_bfe_u32 v72, v59, 16, 1
	v_add3_u32 v72, v59, v72, s70
	ds_write_b16_d16_hi v86, v72 offset:55792
	v_bfe_u32 v72, v52, 16, 1
	v_add3_u32 v72, v52, v72, s70
	ds_write_b16_d16_hi v70, v72 offset:64512
	v_bfe_u32 v72, v53, 16, 1
	v_add3_u32 v72, v53, v72, s70
	ds_write_b16_d16_hi v70, v72 offset:64656
	v_bfe_u32 v72, v54, 16, 1
	v_add3_u32 v72, v54, v72, s70
	ds_write_b16_d16_hi v70, v72 offset:64800
	v_bfe_u32 v72, v55, 16, 1
	v_add3_u32 v72, v55, v72, s70
	ds_write_b16_d16_hi v70, v72 offset:64944
	s_waitcnt vmcnt(0)
	v_bfe_u32 v72, v60, 16, 1
	v_add3_u32 v72, v60, v72, s70
	ds_write_b16_d16_hi v86, v72 offset:64576
	v_bfe_u32 v72, v61, 16, 1
	v_add3_u32 v72, v61, v72, s70
	ds_write_b16_d16_hi v86, v72 offset:64720
	v_bfe_u32 v72, v62, 16, 1
	s_add_i32 s7, s6, s80
	v_add3_u32 v72, v62, v72, s70
	s_cmpk_gt_i32 s7, 0x27f
	ds_write_b16_d16_hi v86, v72 offset:64864
	v_bfe_u32 v72, v63, 16, 1
	s_cselect_b64 s[0:1], -1, 0
	v_add3_u32 v72, v63, v72, s70
	s_and_b64 vcc, exec, s[0:1]
	ds_write_b16_d16_hi v86, v72 offset:65008
	s_waitcnt lgkmcnt(0)
	s_barrier
; __device__ __forceinline__ bf16_t f2bf(float f) { unsigned u = __float_as_uint(f); u += 0x7FFFu + ((u >> 16) & 1u); return (bf16_t)(u >> 16); }
; __device__ __forceinline__ void convert_wt(LAS unsigned char* lds, const float* __restrict__ W, bf16_t* __restrict__ Wt, int K, int N, int mode) {
;     ...
;     int st = blockIdx.x;
;     if (st < nsuper) CW_LOAD(st);
;     for (; st < nsuper; st += gridDim.x) {
;         const int k0 = (st / nsn) * 64, n0 = (st % nsn) * 512;
; #pragma unroll
;         for (int s_ = 0; s_ < 8; ++s_)
; #pragma unroll
;             for (int i_ = 0; i_ < 2; ++i_)
; #pragma unroll
;                 for (int e = 0; e < 4; ++e) T[s_ * 4608 + (c4 + e) * 72 + kk0 + 32 * i_] = f2bf(v[s_ * 2 + i_][e]);
;         __syncthreads();
;         const int nx = st + gridDim.x;
;         if (nx < nsuper) CW_LOAD(nx);
	s_cbranch_vccnz .LBB0_13
	s_mul_hi_i32 s8, s7, 0x66666667
	s_lshr_b32 s9, s8, 31
	s_ashr_i32 s8, s8, 3
	s_add_i32 s9, s8, s9
	v_readlane_b32 s10, v250, 20
	s_mul_i32 s8, s9, 0xffffd800
	s_add_i32 s10, s10, s5
	s_add_i32 s8, s10, s8
	v_lshl_add_u32 v2, s9, 6, v68
	s_ashr_i32 s9, s8, 31
	v_lshl_add_u64 v[0:1], s[8:9], 2, v[64:65]
	v_mad_i64_i32 v[52:53], s[8:9], v2, s63, v[0:1]
	v_add_u32_e32 v2, 32, v2
	v_mad_i64_i32 v[60:61], s[8:9], v2, s63, v[0:1]
	global_load_dwordx4 v[0:3], v[52:53], off
	global_load_dwordx4 v[4:7], v[52:53], off offset:256
	global_load_dwordx4 v[8:11], v[60:61], off
	global_load_dwordx4 v[12:15], v[60:61], off offset:256
	global_load_dwordx4 v[16:19], v[52:53], off offset:512
	global_load_dwordx4 v[20:23], v[52:53], off offset:768
	global_load_dwordx4 v[24:27], v[60:61], off offset:512
	global_load_dwordx4 v[28:31], v[60:61], off offset:768
	global_load_dwordx4 v[32:35], v[52:53], off offset:1024
	global_load_dwordx4 v[36:39], v[52:53], off offset:1280
	global_load_dwordx4 v[40:43], v[60:61], off offset:1024
	global_load_dwordx4 v[44:47], v[60:61], off offset:1280
	global_load_dwordx4 v[48:51], v[52:53], off offset:1536
	s_nop 0
	global_load_dwordx4 v[52:55], v[52:53], off offset:1792
	s_nop 0
	global_load_dwordx4 v[56:59], v[60:61], off offset:1536
	s_nop 0
	global_load_dwordx4 v[60:63], v[60:61], off offset:1792
	s_branch .LBB0_13

; #define LAS __attribute__((address_space(3)))
; __device__ __forceinline__ int fresh_tid() { int t = threadIdx.x; asm volatile("" : "+v"(t)); return t; }
; __device__ __forceinline__ void convert_wt(LAS unsigned char* lds, const float* __restrict__ W, bf16_t* __restrict__ Wt, int K, int N, int mode) {
;     LAS bf16_t* T = (LAS bf16_t*)lds;
;     const int tid = fresh_tid();
;     const int nsn = N / 512, nsuper = (K / 64) * nsn;
;     const int kk0 = tid >> 4, c4 = (tid & 15) * 4;
;     f32x4 v[16];
;     ...
;     int st = blockIdx.x;
;     if (st < nsuper) CW_LOAD(st);
.LBB0_17:
	v_readlane_b32 s6, v250, 30
	v_readlane_b32 s7, v250, 31
	s_lshl_b64 s[4:5], s[4:5], 20
	v_mov_b32_e32 v66, v230
	s_waitcnt vmcnt(23)
	v_cndmask_b32_e64 v0, 0, 1, s[6:7]
	v_cmp_ne_u32_e64 s[0:1], 1, v0
	s_andn2_b64 vcc, exec, s[6:7]
	s_cbranch_vccnz .LBB0_22
	v_readlane_b32 s8, v250, 4
	s_lshl_b64 s[6:7], s[4:5], 2
	v_readlane_b32 s16, v250, 12
	v_lshlrev_b32_e32 v0, 2, v66
	v_readlane_b32 s17, v250, 13
	s_add_u32 s6, s16, s6
	v_and_b32_e32 v71, 60, v0
	v_ashrrev_i32_e32 v68, 4, v66
	s_addc_u32 s7, s17, s7
	v_readlane_b32 s8, v250, 32
	v_lshlrev_b32_e32 v2, 2, v71
	v_mov_b32_e32 v3, v192
	v_add_u32_e32 v0, s8, v68
	v_lshl_add_u64 v[64:65], s[6:7], 0, v[2:3]
	v_readlane_b32 s6, v250, 33
	v_ashrrev_i32_e32 v1, 31, v0
	v_readlane_b32 s7, v250, 34
	v_lshlrev_b64 v[0:1], 13, v[0:1]
	v_ashrrev_i32_e32 v69, 3, v66
	v_lshl_add_u64 v[2:3], s[6:7], 2, v[64:65]
	s_waitcnt vmcnt(10)
	v_lshl_add_u64 v[52:53], v[2:3], 0, v[0:1]
	s_mov_b64 s[6:7], 0x40000
	s_waitcnt vmcnt(9)
	v_add_co_u32_e32 v56, vcc, s71, v52
	s_waitcnt vmcnt(8)
	v_lshl_add_u64 v[60:61], v[52:53], 0, s[6:7]
	v_addc_co_u32_e32 v57, vcc, 0, v53, vcc
	global_load_dwordx4 v[0:3], v[52:53], off
	global_load_dwordx4 v[4:7], v[52:53], off offset:256
	global_load_dwordx4 v[8:11], v[60:61], off offset:256
	global_load_dwordx4 v[12:15], v[60:61], off offset:512
	global_load_dwordx4 v[16:19], v[52:53], off offset:512
	global_load_dwordx4 v[20:23], v[52:53], off offset:768
	global_load_dwordx4 v[24:27], v[60:61], off offset:768
	global_load_dwordx4 v[28:31], v[60:61], off offset:1024
	global_load_dwordx4 v[32:35], v[52:53], off offset:1024
	global_load_dwordx4 v[36:39], v[52:53], off offset:1280
	global_load_dwordx4 v[40:43], v[60:61], off offset:1280
	global_load_dwordx4 v[44:47], v[60:61], off offset:1536
	global_load_dwordx4 v[48:51], v[52:53], off offset:1536
	s_nop 0
	global_load_dwordx4 v[52:55], v[52:53], off offset:1792
	s_nop 0
	global_load_dwordx4 v[56:59], v[56:57], off
	s_nop 0
	global_load_dwordx4 v[60:63], v[60:61], off offset:1792
	v_lshlrev_b32_e32 v66, 4, v66
	v_mul_lo_u32 v67, v69, s64
	v_and_b32_e32 v66, 0x70, v66
	v_readlane_b32 s6, v253, 35
	v_readlane_b32 s9, v250, 5
	v_readlane_b32 s10, v250, 6
	v_lshlrev_b32_e32 v72, 1, v68
	v_add3_u32 v70, 0, v67, v66
	v_mov_b32_e32 v67, v192
	v_readlane_b32 s7, v253, 36
	v_mul_u32_u24_e32 v71, 0x90, v71
	s_lshl_b32 s8, s80, 9
	v_lshl_add_u64 v[66:67], s[6:7], 0, v[66:67]
	v_add3_u32 v71, 0, v72, v71
	s_mov_b32 s9, s8
	s_mov_b32 s10, s75
	v_readlane_b32 s11, v250, 7
	v_readlane_b32 s12, v250, 8
	v_readlane_b32 s13, v250, 9
	v_readlane_b32 s14, v250, 10
	v_readlane_b32 s15, v250, 11
	v_readlane_b32 s18, v250, 14
	v_readlane_b32 s19, v250, 15
	v_readlane_b32 s20, v250, 16
	v_readlane_b32 s21, v250, 17
	v_readlane_b32 s22, v250, 18
	v_readlane_b32 s23, v250, 19
	v_lshrrev_b32_e32 v87, 4, v230
	v_and_b32_e32 v88, 3, v230
	v_lshlrev_b32_e32 v88, 3, v88
	v_xor_b32_e32 v88, v87, v88
	v_sub_u32_e32 v88, v88, v87
	v_bfe_u32 v87, v230, 2, 1
	v_lshlrev_b32_e32 v87, 6, v87
	v_lshl_add_u32 v86, v88, 1, v71
	v_add_u32_e32 v71, v86, v87
	v_sub_u32_e32 v86, v86, v87
	v_and_b32_e32 v87, 7, v230
	v_bfe_u32 v88, v230, 5, 3
	v_xor_b32_e32 v88, v87, v88
	v_sub_u32_e32 v88, v88, v87
	v_lshl_add_u32 v70, v88, 4, v70
	s_branch .LBB0_20

; __device__ __forceinline__ bf16_t f2bf(float f) { unsigned u = __float_as_uint(f); u += 0x7FFFu + ((u >> 16) & 1u); return (bf16_t)(u >> 16); }
; __device__ __forceinline__ void convert_wt(LAS unsigned char* lds, const float* __restrict__ W, bf16_t* __restrict__ Wt, int K, int N, int mode) {
;     ...
;     for (; st < nsuper; st += gridDim.x) {
;         const int k0 = (st / nsn) * 64, n0 = (st % nsn) * 512;
; #pragma unroll
;         for (int s_ = 0; s_ < 8; ++s_)
; #pragma unroll
;             for (int i_ = 0; i_ < 2; ++i_)
; #pragma unroll
;                 for (int e = 0; e < 4; ++e) T[s_ * 4608 + (c4 + e) * 72 + kk0 + 32 * i_] = f2bf(v[s_ * 2 + i_][e]);
;         __syncthreads();
;         const int nx = st + gridDim.x;
;         if (nx < nsuper) CW_LOAD(nx);
.LBB0_20:
	s_waitcnt vmcnt(15)
	v_bfe_u32 v72, v0, 16, 1
	v_add3_u32 v72, v0, v72, s70
	ds_write_b16_d16_hi v71, v72
	v_bfe_u32 v72, v1, 16, 1
	v_add3_u32 v72, v1, v72, s70
	ds_write_b16_d16_hi v71, v72 offset:144
	v_bfe_u32 v72, v2, 16, 1
	v_add3_u32 v72, v2, v72, s70
	ds_write_b16_d16_hi v71, v72 offset:288
	v_bfe_u32 v72, v3, 16, 1
	v_add3_u32 v72, v3, v72, s70
	ds_write_b16_d16_hi v71, v72 offset:432
	s_waitcnt vmcnt(1)
	v_bfe_u32 v72, v56, 16, 1
	v_add3_u32 v72, v56, v72, s70
	ds_write_b16_d16_hi v86, v72 offset:64
	v_bfe_u32 v72, v57, 16, 1
	v_add3_u32 v72, v57, v72, s70
	ds_write_b16_d16_hi v86, v72 offset:208
	v_bfe_u32 v72, v58, 16, 1
	v_add3_u32 v72, v58, v72, s70
	ds_write_b16_d16_hi v86, v72 offset:352
	v_bfe_u32 v72, v59, 16, 1
	v_add3_u32 v72, v59, v72, s70
	ds_write_b16_d16_hi v86, v72 offset:496
	v_bfe_u32 v72, v4, 16, 1
	v_add3_u32 v72, v4, v72, s70
	ds_write_b16_d16_hi v71, v72 offset:9216
	v_bfe_u32 v72, v5, 16, 1
	v_add3_u32 v72, v5, v72, s70
	ds_write_b16_d16_hi v71, v72 offset:9360
	v_bfe_u32 v72, v6, 16, 1
	v_add3_u32 v72, v6, v72, s70
	ds_write_b16_d16_hi v71, v72 offset:9504
	v_bfe_u32 v72, v7, 16, 1
	v_add3_u32 v72, v7, v72, s70
	ds_write_b16_d16_hi v71, v72 offset:9648
	v_bfe_u32 v72, v8, 16, 1
	v_add3_u32 v72, v8, v72, s70
	ds_write_b16_d16_hi v86, v72 offset:9280
	v_bfe_u32 v72, v9, 16, 1
	v_add3_u32 v72, v9, v72, s70
	ds_write_b16_d16_hi v86, v72 offset:9424
	v_bfe_u32 v72, v10, 16, 1
	v_add3_u32 v72, v10, v72, s70
	ds_write_b16_d16_hi v86, v72 offset:9568
	v_bfe_u32 v72, v11, 16, 1
	v_add3_u32 v72, v11, v72, s70
	ds_write_b16_d16_hi v86, v72 offset:9712
	v_bfe_u32 v72, v16, 16, 1
	v_add3_u32 v72, v16, v72, s70
	ds_write_b16_d16_hi v71, v72 offset:18432
	v_bfe_u32 v72, v17, 16, 1
	v_add3_u32 v72, v17, v72, s70
	ds_write_b16_d16_hi v71, v72 offset:18576
	v_bfe_u32 v72, v18, 16, 1
	v_add3_u32 v72, v18, v72, s70
	ds_write_b16_d16_hi v71, v72 offset:18720
	v_bfe_u32 v72, v19, 16, 1
	v_add3_u32 v72, v19, v72, s70
	ds_write_b16_d16_hi v71, v72 offset:18864
	v_bfe_u32 v72, v12, 16, 1
	v_add3_u32 v72, v12, v72, s70
	ds_write_b16_d16_hi v86, v72 offset:18496
	v_bfe_u32 v72, v13, 16, 1
	v_add3_u32 v72, v13, v72, s70
	ds_write_b16_d16_hi v86, v72 offset:18640
	v_bfe_u32 v72, v14, 16, 1
	v_add3_u32 v72, v14, v72, s70
	ds_write_b16_d16_hi v86, v72 offset:18784
	v_bfe_u32 v72, v15, 16, 1
	v_add3_u32 v72, v15, v72, s70
	ds_write_b16_d16_hi v86, v72 offset:18928
	v_bfe_u32 v72, v20, 16, 1
	v_add3_u32 v72, v20, v72, s70
	ds_write_b16_d16_hi v71, v72 offset:27648
	v_bfe_u32 v72, v21, 16, 1
	v_add3_u32 v72, v21, v72, s70
	ds_write_b16_d16_hi v71, v72 offset:27792
	v_bfe_u32 v72, v22, 16, 1
	v_add3_u32 v72, v22, v72, s70
	ds_write_b16_d16_hi v71, v72 offset:27936
	v_bfe_u32 v72, v23, 16, 1
	v_add3_u32 v72, v23, v72, s70
	ds_write_b16_d16_hi v71, v72 offset:28080
	v_bfe_u32 v72, v24, 16, 1
	v_add3_u32 v72, v24, v72, s70
	ds_write_b16_d16_hi v86, v72 offset:27712
	v_bfe_u32 v72, v25, 16, 1
	v_add3_u32 v72, v25, v72, s70
	ds_write_b16_d16_hi v86, v72 offset:27856
	v_bfe_u32 v72, v26, 16, 1
	v_add3_u32 v72, v26, v72, s70
	ds_write_b16_d16_hi v86, v72 offset:28000
	v_bfe_u32 v72, v27, 16, 1
	v_add3_u32 v72, v27, v72, s70
	ds_write_b16_d16_hi v86, v72 offset:28144
	v_bfe_u32 v72, v32, 16, 1
	v_add3_u32 v72, v32, v72, s70
	ds_write_b16_d16_hi v71, v72 offset:36864
	v_bfe_u32 v72, v33, 16, 1
	v_add3_u32 v72, v33, v72, s70
	ds_write_b16_d16_hi v71, v72 offset:37008
	v_bfe_u32 v72, v34, 16, 1
	v_add3_u32 v72, v34, v72, s70
	ds_write_b16_d16_hi v71, v72 offset:37152
	v_bfe_u32 v72, v35, 16, 1
	v_add3_u32 v72, v35, v72, s70
	ds_write_b16_d16_hi v71, v72 offset:37296
	v_bfe_u32 v72, v28, 16, 1
	v_add3_u32 v72, v28, v72, s70
	ds_write_b16_d16_hi v86, v72 offset:36928
	v_bfe_u32 v72, v29, 16, 1
	v_add3_u32 v72, v29, v72, s70
	ds_write_b16_d16_hi v86, v72 offset:37072
	v_bfe_u32 v72, v30, 16, 1
	v_add3_u32 v72, v30, v72, s70
	ds_write_b16_d16_hi v86, v72 offset:37216
	v_bfe_u32 v72, v31, 16, 1
	v_add3_u32 v72, v31, v72, s70
	ds_write_b16_d16_hi v86, v72 offset:37360
	v_bfe_u32 v72, v36, 16, 1
	v_add3_u32 v72, v36, v72, s70
	ds_write_b16_d16_hi v71, v72 offset:46080
	v_bfe_u32 v72, v37, 16, 1
	v_add3_u32 v72, v37, v72, s70
	ds_write_b16_d16_hi v71, v72 offset:46224
	v_bfe_u32 v72, v38, 16, 1
	v_add3_u32 v72, v38, v72, s70
	ds_write_b16_d16_hi v71, v72 offset:46368
	v_bfe_u32 v72, v39, 16, 1
	v_add3_u32 v72, v39, v72, s70
	ds_write_b16_d16_hi v71, v72 offset:46512
	v_bfe_u32 v72, v40, 16, 1
	v_add3_u32 v72, v40, v72, s70
	ds_write_b16_d16_hi v86, v72 offset:46144
	v_bfe_u32 v72, v41, 16, 1
	v_add3_u32 v72, v41, v72, s70
	ds_write_b16_d16_hi v86, v72 offset:46288
	v_bfe_u32 v72, v42, 16, 1
	v_add3_u32 v72, v42, v72, s70
	ds_write_b16_d16_hi v86, v72 offset:46432
	v_bfe_u32 v72, v43, 16, 1
	v_add3_u32 v72, v43, v72, s70
	ds_write_b16_d16_hi v86, v72 offset:46576
	v_bfe_u32 v72, v48, 16, 1
	v_add3_u32 v72, v48, v72, s70
	ds_write_b16_d16_hi v71, v72 offset:55296
	v_bfe_u32 v72, v49, 16, 1
	v_add3_u32 v72, v49, v72, s70
	ds_write_b16_d16_hi v71, v72 offset:55440
	v_bfe_u32 v72, v50, 16, 1
	v_add3_u32 v72, v50, v72, s70
	ds_write_b16_d16_hi v71, v72 offset:55584
	v_bfe_u32 v72, v51, 16, 1
	v_add3_u32 v72, v51, v72, s70
	ds_write_b16_d16_hi v71, v72 offset:55728
	v_bfe_u32 v72, v44, 16, 1
	v_add3_u32 v72, v44, v72, s70
	ds_write_b16_d16_hi v86, v72 offset:55360
	v_bfe_u32 v72, v45, 16, 1
	v_add3_u32 v72, v45, v72, s70
	ds_write_b16_d16_hi v86, v72 offset:55504
	v_bfe_u32 v72, v46, 16, 1
	v_add3_u32 v72, v46, v72, s70
	ds_write_b16_d16_hi v86, v72 offset:55648
	v_bfe_u32 v72, v47, 16, 1
	v_add3_u32 v72, v47, v72, s70
	ds_write_b16_d16_hi v86, v72 offset:55792
	v_bfe_u32 v72, v52, 16, 1
	v_add3_u32 v72, v52, v72, s70
	ds_write_b16_d16_hi v71, v72 offset:64512
	v_bfe_u32 v72, v53, 16, 1
	v_add3_u32 v72, v53, v72, s70
	ds_write_b16_d16_hi v71, v72 offset:64656
	v_bfe_u32 v72, v54, 16, 1
	v_add3_u32 v72, v54, v72, s70
	ds_write_b16_d16_hi v71, v72 offset:64800
	v_bfe_u32 v72, v55, 16, 1
	v_add3_u32 v72, v55, v72, s70
	ds_write_b16_d16_hi v71, v72 offset:64944
	s_waitcnt vmcnt(0)
	v_bfe_u32 v72, v60, 16, 1
	v_add3_u32 v72, v60, v72, s70
	ds_write_b16_d16_hi v86, v72 offset:64576
	v_bfe_u32 v72, v61, 16, 1
	v_add3_u32 v72, v61, v72, s70
	ds_write_b16_d16_hi v86, v72 offset:64720
	v_bfe_u32 v72, v62, 16, 1
	s_add_i32 s11, s10, s80
	v_add3_u32 v72, v62, v72, s70
	s_cmp_gt_i32 s11, 31
	ds_write_b16_d16_hi v86, v72 offset:64864
	v_bfe_u32 v72, v63, 16, 1
	s_cselect_b64 s[6:7], -1, 0
	v_add3_u32 v72, v63, v72, s70
	s_and_b64 vcc, exec, s[6:7]
	ds_write_b16_d16_hi v86, v72 offset:65008
	s_waitcnt lgkmcnt(0)
	s_barrier
; #define LAS __attribute__((address_space(3)))
; __device__ __forceinline__ bf16_t f2bf(float f) { unsigned u = __float_as_uint(f); u += 0x7FFFu + ((u >> 16) & 1u); return (bf16_t)(u >> 16); }
; __device__ __forceinline__ int fresh_tid() { int t = threadIdx.x; asm volatile("" : "+v"(t)); return t; }
; __device__ __forceinline__ void convert_wt(LAS unsigned char* lds, const float* __restrict__ W, bf16_t* __restrict__ Wt, int K, int N, int mode) {
;     LAS bf16_t* T = (LAS bf16_t*)lds;
;     const int tid = fresh_tid();
;     const int nsn = N / 512, nsuper = (K / 64) * nsn;
;     const int kk0 = tid >> 4, c4 = (tid & 15) * 4;
;     f32x4 v[16];
;     ...
;     int st = blockIdx.x;
;     if (st < nsuper) CW_LOAD(st);
;     for (; st < nsuper; st += gridDim.x) {
;         const int k0 = (st / nsn) * 64, n0 = (st % nsn) * 512;
; #pragma unroll
;         for (int s_ = 0; s_ < 8; ++s_)
; #pragma unroll
;             for (int i_ = 0; i_ < 2; ++i_)
; #pragma unroll
;                 for (int e = 0; e < 4; ++e) T[s_ * 4608 + (c4 + e) * 72 + kk0 + 32 * i_] = f2bf(v[s_ * 2 + i_][e]);
;         __syncthreads();
;         const int nx = st + gridDim.x;
;         if (nx < nsuper) CW_LOAD(nx);
;         { const int n = tid >> 3, k8 = (tid & 7) * 8;
; #pragma unroll
;           for (int s_ = 0; s_ < 8; ++s_) { const u32x4 w = *(const LAS u32x4*)(T + s_ * 4608 + n * 72 + k8);
;               *(u32x4*)(Wt + (size_t)(n0 + s_ * 64 + n) * K + k0 + k8) = w; } }
	s_cbranch_vccnz .LBB0_19
	s_ashr_i32 s12, s11, 31
	s_lshr_b32 s12, s12, 30
	s_add_i32 s12, s11, s12
	s_ashr_i32 s13, s12, 2
	v_readlane_b32 s12, v250, 20
	s_add_i32 s12, s12, s9
	s_lshl_b32 s14, s13, 11
	s_sub_i32 s12, s12, s14
	v_lshl_add_u32 v0, s13, 6, v68
	v_ashrrev_i32_e32 v1, 31, v0
	s_ashr_i32 s13, s12, 31
	v_lshl_add_u64 v[2:3], s[12:13], 2, v[64:65]
	v_lshlrev_b64 v[0:1], 13, v[0:1]
	v_lshl_add_u64 v[52:53], v[2:3], 0, v[0:1]
	s_mov_b64 s[12:13], 0x40000
	v_add_co_u32_e32 v56, vcc, s71, v52
	v_lshl_add_u64 v[60:61], v[52:53], 0, s[12:13]
	s_nop 0
	v_addc_co_u32_e32 v57, vcc, 0, v53, vcc
	global_load_dwordx4 v[0:3], v[52:53], off
	global_load_dwordx4 v[4:7], v[52:53], off offset:256
	global_load_dwordx4 v[8:11], v[60:61], off offset:256
	global_load_dwordx4 v[12:15], v[60:61], off offset:512
	global_load_dwordx4 v[16:19], v[52:53], off offset:512
	global_load_dwordx4 v[20:23], v[52:53], off offset:768
	global_load_dwordx4 v[24:27], v[60:61], off offset:768
	global_load_dwordx4 v[28:31], v[60:61], off offset:1024
	global_load_dwordx4 v[32:35], v[52:53], off offset:1024
	global_load_dwordx4 v[36:39], v[52:53], off offset:1280
	global_load_dwordx4 v[40:43], v[60:61], off offset:1280
	global_load_dwordx4 v[44:47], v[60:61], off offset:1536
	global_load_dwordx4 v[48:51], v[52:53], off offset:1536
	s_nop 0
	global_load_dwordx4 v[52:55], v[52:53], off offset:1792
	s_nop 0
	global_load_dwordx4 v[56:59], v[56:57], off
	s_nop 0
	global_load_dwordx4 v[60:63], v[60:61], off offset:1792
	s_branch .LBB0_19
.LBB0_22:
	v_mov_b32_e32 v66, v230
	s_and_b64 vcc, exec, s[0:1]
	s_cbranch_vccnz .LBB0_27
	s_lshl_b64 s[0:1], s[4:5], 2
	v_readlane_b32 s4, v250, 4
	v_readlane_b32 s14, v250, 14
	s_waitcnt vmcnt(23)
	v_lshlrev_b32_e32 v0, 2, v66
	v_readlane_b32 s15, v250, 15
	s_add_u32 s0, s14, s0
	v_and_b32_e32 v71, 60, v0
	v_ashrrev_i32_e32 v68, 4, v66
	s_addc_u32 s1, s15, s1
	v_readlane_b32 s4, v250, 32
	v_lshlrev_b32_e32 v2, 2, v71
	v_mov_b32_e32 v3, v192
	v_add_u32_e32 v0, s4, v68
	v_lshl_add_u64 v[64:65], s[0:1], 0, v[2:3]
	v_readlane_b32 s0, v250, 33
	v_ashrrev_i32_e32 v1, 31, v0
	v_readlane_b32 s1, v250, 34
	v_lshlrev_b64 v[0:1], 13, v[0:1]
	v_ashrrev_i32_e32 v69, 3, v66
	v_lshl_add_u64 v[2:3], s[0:1], 2, v[64:65]
	s_waitcnt vmcnt(10)
	v_lshl_add_u64 v[52:53], v[2:3], 0, v[0:1]
	s_mov_b64 s[0:1], 0x40000
	s_waitcnt vmcnt(9)
	v_add_co_u32_e32 v56, vcc, s71, v52
	s_waitcnt vmcnt(8)
	v_lshl_add_u64 v[60:61], v[52:53], 0, s[0:1]
	v_addc_co_u32_e32 v57, vcc, 0, v53, vcc
	global_load_dwordx4 v[0:3], v[52:53], off
	global_load_dwordx4 v[4:7], v[52:53], off offset:256
	global_load_dwordx4 v[8:11], v[60:61], off offset:256
	global_load_dwordx4 v[12:15], v[60:61], off offset:512
	global_load_dwordx4 v[16:19], v[52:53], off offset:512
	global_load_dwordx4 v[20:23], v[52:53], off offset:768
	global_load_dwordx4 v[24:27], v[60:61], off offset:768
	global_load_dwordx4 v[28:31], v[60:61], off offset:1024
	global_load_dwordx4 v[32:35], v[52:53], off offset:1024
	global_load_dwordx4 v[36:39], v[52:53], off offset:1280
	global_load_dwordx4 v[40:43], v[60:61], off offset:1280
	global_load_dwordx4 v[44:47], v[60:61], off offset:1536
	global_load_dwordx4 v[48:51], v[52:53], off offset:1536
	s_nop 0
	global_load_dwordx4 v[52:55], v[52:53], off offset:1792
	s_nop 0
	global_load_dwordx4 v[56:59], v[56:57], off
	s_nop 0
	global_load_dwordx4 v[60:63], v[60:61], off offset:1792
	v_lshlrev_b32_e32 v66, 4, v66
	v_mul_lo_u32 v67, v69, s64
	v_and_b32_e32 v66, 0x70, v66
	v_readlane_b32 s0, v250, 35
	v_readlane_b32 s5, v250, 5
	v_readlane_b32 s6, v250, 6
	v_lshlrev_b32_e32 v72, 1, v68
	v_add3_u32 v70, 0, v67, v66
	v_mov_b32_e32 v67, v192
	v_readlane_b32 s1, v250, 36
	v_mul_u32_u24_e32 v71, 0x90, v71
	s_lshl_b32 s4, s80, 9
	v_lshl_add_u64 v[66:67], s[0:1], 0, v[66:67]
	v_add3_u32 v71, 0, v72, v71
	s_mov_b32 s5, s4
	s_mov_b32 s6, s75
	v_readlane_b32 s7, v250, 7
	v_readlane_b32 s8, v250, 8
	v_readlane_b32 s9, v250, 9
	v_readlane_b32 s10, v250, 10
	v_readlane_b32 s11, v250, 11
	v_readlane_b32 s12, v250, 12
	v_readlane_b32 s13, v250, 13
	v_readlane_b32 s16, v250, 16
	v_readlane_b32 s17, v250, 17
	v_readlane_b32 s18, v250, 18
	v_readlane_b32 s19, v250, 19
	v_lshrrev_b32_e32 v87, 4, v230
	v_and_b32_e32 v88, 3, v230
	v_lshlrev_b32_e32 v88, 3, v88
	v_xor_b32_e32 v88, v87, v88
	v_sub_u32_e32 v88, v88, v87
	v_bfe_u32 v87, v230, 2, 1
	v_lshlrev_b32_e32 v87, 6, v87
	v_lshl_add_u32 v86, v88, 1, v71
	v_add_u32_e32 v71, v86, v87
	v_sub_u32_e32 v86, v86, v87
	v_and_b32_e32 v87, 7, v230
	v_bfe_u32 v88, v230, 5, 3
	v_xor_b32_e32 v88, v87, v88
	v_sub_u32_e32 v88, v88, v87
	v_lshl_add_u32 v70, v88, 4, v70
	s_branch .LBB0_25

; __device__ __forceinline__ bf16_t f2bf(float f) { unsigned u = __float_as_uint(f); u += 0x7FFFu + ((u >> 16) & 1u); return (bf16_t)(u >> 16); }
; __device__ __forceinline__ void convert_wt(LAS unsigned char* lds, const float* __restrict__ W, bf16_t* __restrict__ Wt, int K, int N, int mode) {
;     ...
;     for (; st < nsuper; st += gridDim.x) {
;         const int k0 = (st / nsn) * 64, n0 = (st % nsn) * 512;
; #pragma unroll
;         for (int s_ = 0; s_ < 8; ++s_)
; #pragma unroll
;             for (int i_ = 0; i_ < 2; ++i_)
; #pragma unroll
;                 for (int e = 0; e < 4; ++e) T[s_ * 4608 + (c4 + e) * 72 + kk0 + 32 * i_] = f2bf(v[s_ * 2 + i_][e]);
;         __syncthreads();
;         const int nx = st + gridDim.x;
;         if (nx < nsuper) CW_LOAD(nx);
.LBB0_25:
	s_waitcnt vmcnt(15)
	v_bfe_u32 v72, v0, 16, 1
	v_add3_u32 v72, v0, v72, s70
	ds_write_b16_d16_hi v71, v72
	v_bfe_u32 v72, v1, 16, 1
	v_add3_u32 v72, v1, v72, s70
	ds_write_b16_d16_hi v71, v72 offset:144
	v_bfe_u32 v72, v2, 16, 1
	v_add3_u32 v72, v2, v72, s70
	ds_write_b16_d16_hi v71, v72 offset:288
	v_bfe_u32 v72, v3, 16, 1
	v_add3_u32 v72, v3, v72, s70
	ds_write_b16_d16_hi v71, v72 offset:432
	s_waitcnt vmcnt(1)
	v_bfe_u32 v72, v56, 16, 1
	v_add3_u32 v72, v56, v72, s70
	ds_write_b16_d16_hi v86, v72 offset:64
	v_bfe_u32 v72, v57, 16, 1
	v_add3_u32 v72, v57, v72, s70
	ds_write_b16_d16_hi v86, v72 offset:208
	v_bfe_u32 v72, v58, 16, 1
	v_add3_u32 v72, v58, v72, s70
	ds_write_b16_d16_hi v86, v72 offset:352
	v_bfe_u32 v72, v59, 16, 1
	v_add3_u32 v72, v59, v72, s70
	ds_write_b16_d16_hi v86, v72 offset:496
	v_bfe_u32 v72, v4, 16, 1
	v_add3_u32 v72, v4, v72, s70
	ds_write_b16_d16_hi v71, v72 offset:9216
	v_bfe_u32 v72, v5, 16, 1
	v_add3_u32 v72, v5, v72, s70
	ds_write_b16_d16_hi v71, v72 offset:9360
	v_bfe_u32 v72, v6, 16, 1
	v_add3_u32 v72, v6, v72, s70
	ds_write_b16_d16_hi v71, v72 offset:9504
	v_bfe_u32 v72, v7, 16, 1
	v_add3_u32 v72, v7, v72, s70
	ds_write_b16_d16_hi v71, v72 offset:9648
	v_bfe_u32 v72, v8, 16, 1
	v_add3_u32 v72, v8, v72, s70
	ds_write_b16_d16_hi v86, v72 offset:9280
	v_bfe_u32 v72, v9, 16, 1
	v_add3_u32 v72, v9, v72, s70
	ds_write_b16_d16_hi v86, v72 offset:9424
	v_bfe_u32 v72, v10, 16, 1
	v_add3_u32 v72, v10, v72, s70
	ds_write_b16_d16_hi v86, v72 offset:9568
	v_bfe_u32 v72, v11, 16, 1
	v_add3_u32 v72, v11, v72, s70
	ds_write_b16_d16_hi v86, v72 offset:9712
	v_bfe_u32 v72, v16, 16, 1
	v_add3_u32 v72, v16, v72, s70
	ds_write_b16_d16_hi v71, v72 offset:18432
	v_bfe_u32 v72, v17, 16, 1
	v_add3_u32 v72, v17, v72, s70
	ds_write_b16_d16_hi v71, v72 offset:18576
	v_bfe_u32 v72, v18, 16, 1
	v_add3_u32 v72, v18, v72, s70
	ds_write_b16_d16_hi v71, v72 offset:18720
	v_bfe_u32 v72, v19, 16, 1
	v_add3_u32 v72, v19, v72, s70
	ds_write_b16_d16_hi v71, v72 offset:18864
	v_bfe_u32 v72, v12, 16, 1
	v_add3_u32 v72, v12, v72, s70
	ds_write_b16_d16_hi v86, v72 offset:18496
	v_bfe_u32 v72, v13, 16, 1
	v_add3_u32 v72, v13, v72, s70
	ds_write_b16_d16_hi v86, v72 offset:18640
	v_bfe_u32 v72, v14, 16, 1
	v_add3_u32 v72, v14, v72, s70
	ds_write_b16_d16_hi v86, v72 offset:18784
	v_bfe_u32 v72, v15, 16, 1
	v_add3_u32 v72, v15, v72, s70
	ds_write_b16_d16_hi v86, v72 offset:18928
	v_bfe_u32 v72, v20, 16, 1
	v_add3_u32 v72, v20, v72, s70
	ds_write_b16_d16_hi v71, v72 offset:27648
	v_bfe_u32 v72, v21, 16, 1
	v_add3_u32 v72, v21, v72, s70
	ds_write_b16_d16_hi v71, v72 offset:27792
	v_bfe_u32 v72, v22, 16, 1
	v_add3_u32 v72, v22, v72, s70
	ds_write_b16_d16_hi v71, v72 offset:27936
	v_bfe_u32 v72, v23, 16, 1
	v_add3_u32 v72, v23, v72, s70
	ds_write_b16_d16_hi v71, v72 offset:28080
	v_bfe_u32 v72, v24, 16, 1
	v_add3_u32 v72, v24, v72, s70
	ds_write_b16_d16_hi v86, v72 offset:27712
	v_bfe_u32 v72, v25, 16, 1
	v_add3_u32 v72, v25, v72, s70
	ds_write_b16_d16_hi v86, v72 offset:27856
	v_bfe_u32 v72, v26, 16, 1
	v_add3_u32 v72, v26, v72, s70
	ds_write_b16_d16_hi v86, v72 offset:28000
	v_bfe_u32 v72, v27, 16, 1
	v_add3_u32 v72, v27, v72, s70
	ds_write_b16_d16_hi v86, v72 offset:28144
	v_bfe_u32 v72, v32, 16, 1
	v_add3_u32 v72, v32, v72, s70
	ds_write_b16_d16_hi v71, v72 offset:36864
	v_bfe_u32 v72, v33, 16, 1
	v_add3_u32 v72, v33, v72, s70
	ds_write_b16_d16_hi v71, v72 offset:37008
	v_bfe_u32 v72, v34, 16, 1
	v_add3_u32 v72, v34, v72, s70
	ds_write_b16_d16_hi v71, v72 offset:37152
	v_bfe_u32 v72, v35, 16, 1
	v_add3_u32 v72, v35, v72, s70
	ds_write_b16_d16_hi v71, v72 offset:37296
	v_bfe_u32 v72, v28, 16, 1
	v_add3_u32 v72, v28, v72, s70
	ds_write_b16_d16_hi v86, v72 offset:36928
	v_bfe_u32 v72, v29, 16, 1
	v_add3_u32 v72, v29, v72, s70
	ds_write_b16_d16_hi v86, v72 offset:37072
	v_bfe_u32 v72, v30, 16, 1
	v_add3_u32 v72, v30, v72, s70
	ds_write_b16_d16_hi v86, v72 offset:37216
	v_bfe_u32 v72, v31, 16, 1
	v_add3_u32 v72, v31, v72, s70
	ds_write_b16_d16_hi v86, v72 offset:37360
	v_bfe_u32 v72, v36, 16, 1
	v_add3_u32 v72, v36, v72, s70
	ds_write_b16_d16_hi v71, v72 offset:46080
	v_bfe_u32 v72, v37, 16, 1
	v_add3_u32 v72, v37, v72, s70
	ds_write_b16_d16_hi v71, v72 offset:46224
	v_bfe_u32 v72, v38, 16, 1
	v_add3_u32 v72, v38, v72, s70
	ds_write_b16_d16_hi v71, v72 offset:46368
	v_bfe_u32 v72, v39, 16, 1
	v_add3_u32 v72, v39, v72, s70
	ds_write_b16_d16_hi v71, v72 offset:46512
	v_bfe_u32 v72, v40, 16, 1
	v_add3_u32 v72, v40, v72, s70
	ds_write_b16_d16_hi v86, v72 offset:46144
	v_bfe_u32 v72, v41, 16, 1
	v_add3_u32 v72, v41, v72, s70
	ds_write_b16_d16_hi v86, v72 offset:46288
	v_bfe_u32 v72, v42, 16, 1
	v_add3_u32 v72, v42, v72, s70
	ds_write_b16_d16_hi v86, v72 offset:46432
	v_bfe_u32 v72, v43, 16, 1
	v_add3_u32 v72, v43, v72, s70
	ds_write_b16_d16_hi v86, v72 offset:46576
	v_bfe_u32 v72, v48, 16, 1
	v_add3_u32 v72, v48, v72, s70
	ds_write_b16_d16_hi v71, v72 offset:55296
	v_bfe_u32 v72, v49, 16, 1
	v_add3_u32 v72, v49, v72, s70
	ds_write_b16_d16_hi v71, v72 offset:55440
	v_bfe_u32 v72, v50, 16, 1
	v_add3_u32 v72, v50, v72, s70
	ds_write_b16_d16_hi v71, v72 offset:55584
	v_bfe_u32 v72, v51, 16, 1
	v_add3_u32 v72, v51, v72, s70
	ds_write_b16_d16_hi v71, v72 offset:55728
	v_bfe_u32 v72, v44, 16, 1
	v_add3_u32 v72, v44, v72, s70
	ds_write_b16_d16_hi v86, v72 offset:55360
	v_bfe_u32 v72, v45, 16, 1
	v_add3_u32 v72, v45, v72, s70
	ds_write_b16_d16_hi v86, v72 offset:55504
	v_bfe_u32 v72, v46, 16, 1
	v_add3_u32 v72, v46, v72, s70
	ds_write_b16_d16_hi v86, v72 offset:55648
	v_bfe_u32 v72, v47, 16, 1
	v_add3_u32 v72, v47, v72, s70
	ds_write_b16_d16_hi v86, v72 offset:55792
	v_bfe_u32 v72, v52, 16, 1
	v_add3_u32 v72, v52, v72, s70
	ds_write_b16_d16_hi v71, v72 offset:64512
	v_bfe_u32 v72, v53, 16, 1
	v_add3_u32 v72, v53, v72, s70
	ds_write_b16_d16_hi v71, v72 offset:64656
	v_bfe_u32 v72, v54, 16, 1
	v_add3_u32 v72, v54, v72, s70
	ds_write_b16_d16_hi v71, v72 offset:64800
	v_bfe_u32 v72, v55, 16, 1
	v_add3_u32 v72, v55, v72, s70
	ds_write_b16_d16_hi v71, v72 offset:64944
	s_waitcnt vmcnt(0)
	v_bfe_u32 v72, v60, 16, 1
	v_add3_u32 v72, v60, v72, s70
	ds_write_b16_d16_hi v86, v72 offset:64576
	v_bfe_u32 v72, v61, 16, 1
	v_add3_u32 v72, v61, v72, s70
	ds_write_b16_d16_hi v86, v72 offset:64720
	v_bfe_u32 v72, v62, 16, 1
	s_add_i32 s7, s6, s80
	v_add3_u32 v72, v62, v72, s70
	s_cmp_gt_i32 s7, 31
	ds_write_b16_d16_hi v86, v72 offset:64864
	v_bfe_u32 v72, v63, 16, 1
	s_cselect_b64 s[0:1], -1, 0
	v_add3_u32 v72, v63, v72, s70
	s_and_b64 vcc, exec, s[0:1]
	ds_write_b16_d16_hi v86, v72 offset:65008
	s_waitcnt lgkmcnt(0)
	s_barrier
; #define LAS __attribute__((address_space(3)))
; __device__ __forceinline__ bf16_t f2bf(float f) { unsigned u = __float_as_uint(f); u += 0x7FFFu + ((u >> 16) & 1u); return (bf16_t)(u >> 16); }
; __device__ __forceinline__ int fresh_tid() { int t = threadIdx.x; asm volatile("" : "+v"(t)); return t; }
; __device__ __forceinline__ void convert_wt(LAS unsigned char* lds, const float* __restrict__ W, bf16_t* __restrict__ Wt, int K, int N, int mode) {
;     LAS bf16_t* T = (LAS bf16_t*)lds;
;     const int tid = fresh_tid();
;     const int nsn = N / 512, nsuper = (K / 64) * nsn;
;     const int kk0 = tid >> 4, c4 = (tid & 15) * 4;
;     f32x4 v[16];
;     ...
;     int st = blockIdx.x;
;     if (st < nsuper) CW_LOAD(st);
;     for (; st < nsuper; st += gridDim.x) {
;         const int k0 = (st / nsn) * 64, n0 = (st % nsn) * 512;
; #pragma unroll
;         for (int s_ = 0; s_ < 8; ++s_)
; #pragma unroll
;             for (int i_ = 0; i_ < 2; ++i_)
; #pragma unroll
;                 for (int e = 0; e < 4; ++e) T[s_ * 4608 + (c4 + e) * 72 + kk0 + 32 * i_] = f2bf(v[s_ * 2 + i_][e]);
;         __syncthreads();
;         const int nx = st + gridDim.x;
;         if (nx < nsuper) CW_LOAD(nx);
;         { const int n = tid >> 3, k8 = (tid & 7) * 8;
; #pragma unroll
;           for (int s_ = 0; s_ < 8; ++s_) { const u32x4 w = *(const LAS u32x4*)(T + s_ * 4608 + n * 72 + k8);
;               *(u32x4*)(Wt + (size_t)(n0 + s_ * 64 + n) * K + k0 + k8) = w; } }
	s_cbranch_vccnz .LBB0_24
	s_ashr_i32 s8, s7, 31
	s_lshr_b32 s8, s8, 30
	s_add_i32 s8, s7, s8
	s_ashr_i32 s9, s8, 2
	v_readlane_b32 s8, v250, 20
	s_add_i32 s8, s8, s5
	s_lshl_b32 s10, s9, 11
	s_sub_i32 s8, s8, s10
	v_lshl_add_u32 v0, s9, 6, v68
	v_ashrrev_i32_e32 v1, 31, v0
	s_ashr_i32 s9, s8, 31
	v_lshl_add_u64 v[2:3], s[8:9], 2, v[64:65]
	v_lshlrev_b64 v[0:1], 13, v[0:1]
	v_lshl_add_u64 v[52:53], v[2:3], 0, v[0:1]
	s_mov_b64 s[8:9], 0x40000
	v_add_co_u32_e32 v56, vcc, s71, v52
	v_lshl_add_u64 v[60:61], v[52:53], 0, s[8:9]
	s_nop 0
	v_addc_co_u32_e32 v57, vcc, 0, v53, vcc
	global_load_dwordx4 v[0:3], v[52:53], off
	global_load_dwordx4 v[4:7], v[52:53], off offset:256
	global_load_dwordx4 v[8:11], v[60:61], off offset:256
	global_load_dwordx4 v[12:15], v[60:61], off offset:512
	global_load_dwordx4 v[16:19], v[52:53], off offset:512
	global_load_dwordx4 v[20:23], v[52:53], off offset:768
	global_load_dwordx4 v[24:27], v[60:61], off offset:768
	global_load_dwordx4 v[28:31], v[60:61], off offset:1024
	global_load_dwordx4 v[32:35], v[52:53], off offset:1024
	global_load_dwordx4 v[36:39], v[52:53], off offset:1280
	global_load_dwordx4 v[40:43], v[60:61], off offset:1280
	global_load_dwordx4 v[44:47], v[60:61], off offset:1536
	global_load_dwordx4 v[48:51], v[52:53], off offset:1536
	s_nop 0
	global_load_dwordx4 v[52:55], v[52:53], off offset:1792
	s_nop 0
	global_load_dwordx4 v[56:59], v[56:57], off
	s_nop 0
	global_load_dwordx4 v[60:63], v[60:61], off offset:1792
	s_branch .LBB0_24
.LBB0_27:
	v_readlane_b32 s4, v250, 37
	v_readlane_b32 s0, v251, 38
	v_readlane_b32 s5, v250, 38
	v_readlane_b32 s1, v251, 39
	s_lshl_b64 s[0:1], s[0:1], 22
	s_waitcnt vmcnt(23)
	v_cndmask_b32_e64 v0, 0, 1, s[4:5]
	v_mov_b32_e32 v66, v230
	v_cmp_ne_u32_e64 s[38:39], 1, v0
	s_andn2_b64 vcc, exec, s[4:5]
	s_cbranch_vccnz .LBB0_32
	v_readlane_b32 s8, v250, 4
	s_lshl_b64 s[4:5], s[0:1], 2
	v_readlane_b32 s20, v250, 16
	v_lshlrev_b32_e32 v0, 2, v66
	v_readlane_b32 s21, v250, 17
	s_add_u32 s4, s20, s4
	v_and_b32_e32 v71, 60, v0
	v_ashrrev_i32_e32 v68, 4, v66
	s_addc_u32 s5, s21, s5
	v_readlane_b32 s6, v250, 32
	v_lshlrev_b32_e32 v2, 2, v71
	v_mov_b32_e32 v3, v192
	v_add_u32_e32 v0, s6, v68
	v_lshl_add_u64 v[64:65], s[4:5], 0, v[2:3]
	v_readlane_b32 s4, v250, 33
	v_ashrrev_i32_e32 v1, 31, v0
	v_readlane_b32 s5, v250, 34
	v_lshlrev_b64 v[0:1], 13, v[0:1]
	v_ashrrev_i32_e32 v69, 3, v66
	v_lshl_add_u64 v[2:3], s[4:5], 2, v[64:65]
	s_waitcnt vmcnt(10)
	v_lshl_add_u64 v[52:53], v[2:3], 0, v[0:1]
	s_mov_b64 s[4:5], 0x40000
	s_waitcnt vmcnt(9)
	v_add_co_u32_e32 v56, vcc, s71, v52
	s_waitcnt vmcnt(8)
	v_lshl_add_u64 v[60:61], v[52:53], 0, s[4:5]
	v_addc_co_u32_e32 v57, vcc, 0, v53, vcc
	global_load_dwordx4 v[0:3], v[52:53], off
	global_load_dwordx4 v[4:7], v[52:53], off offset:256
	global_load_dwordx4 v[8:11], v[60:61], off offset:256
	global_load_dwordx4 v[12:15], v[60:61], off offset:512
	global_load_dwordx4 v[16:19], v[52:53], off offset:512
	global_load_dwordx4 v[20:23], v[52:53], off offset:768
	global_load_dwordx4 v[24:27], v[60:61], off offset:768
	global_load_dwordx4 v[28:31], v[60:61], off offset:1024
	global_load_dwordx4 v[32:35], v[52:53], off offset:1024
	global_load_dwordx4 v[36:39], v[52:53], off offset:1280
	global_load_dwordx4 v[40:43], v[60:61], off offset:1280
	global_load_dwordx4 v[44:47], v[60:61], off offset:1536
	global_load_dwordx4 v[48:51], v[52:53], off offset:1536
	s_nop 0
	global_load_dwordx4 v[52:55], v[52:53], off offset:1792
	s_nop 0
	global_load_dwordx4 v[56:59], v[56:57], off
	s_nop 0
	global_load_dwordx4 v[60:63], v[60:61], off offset:1792
	v_lshlrev_b32_e32 v66, 4, v66
	v_mul_lo_u32 v67, v69, s64
	v_and_b32_e32 v66, 0x70, v66
	v_lshlrev_b32_e32 v72, 1, v68
	v_add3_u32 v70, 0, v67, v66
	v_mov_b32_e32 v67, v192
	v_mul_u32_u24_e32 v71, 0x90, v71
	s_lshl_b32 s6, s80, 9
	v_lshl_add_u64 v[66:67], s[44:45], 0, v[66:67]
	v_add3_u32 v71, 0, v72, v71
	s_mov_b32 s7, s6
	s_mov_b32 s8, s75
	v_readlane_b32 s9, v250, 5
	v_readlane_b32 s10, v250, 6
	v_readlane_b32 s11, v250, 7
	v_readlane_b32 s12, v250, 8
	v_readlane_b32 s13, v250, 9
	v_readlane_b32 s14, v250, 10
	v_readlane_b32 s15, v250, 11
	v_readlane_b32 s16, v250, 12
	v_readlane_b32 s17, v250, 13
	v_readlane_b32 s18, v250, 14
	v_readlane_b32 s19, v250, 15
	v_readlane_b32 s22, v250, 18
	v_readlane_b32 s23, v250, 19
	v_lshrrev_b32_e32 v87, 4, v230
	v_and_b32_e32 v88, 3, v230
	v_lshlrev_b32_e32 v88, 3, v88
	v_xor_b32_e32 v88, v87, v88
	v_sub_u32_e32 v88, v88, v87
	v_bfe_u32 v87, v230, 2, 1
	v_lshlrev_b32_e32 v87, 6, v87
	v_lshl_add_u32 v86, v88, 1, v71
	v_add_u32_e32 v71, v86, v87
	v_sub_u32_e32 v86, v86, v87
	v_and_b32_e32 v87, 7, v230
	v_bfe_u32 v88, v230, 5, 3
	v_xor_b32_e32 v88, v87, v88
	v_sub_u32_e32 v88, v88, v87
	v_lshl_add_u32 v70, v88, 4, v70
	s_branch .LBB0_30

; __device__ __forceinline__ bf16_t f2bf(float f) { unsigned u = __float_as_uint(f); u += 0x7FFFu + ((u >> 16) & 1u); return (bf16_t)(u >> 16); }
; __device__ __forceinline__ void convert_wt(LAS unsigned char* lds, const float* __restrict__ W, bf16_t* __restrict__ Wt, int K, int N, int mode) {
;     ...
;     for (; st < nsuper; st += gridDim.x) {
;         const int k0 = (st / nsn) * 64, n0 = (st % nsn) * 512;
; #pragma unroll
;         for (int s_ = 0; s_ < 8; ++s_)
; #pragma unroll
;             for (int i_ = 0; i_ < 2; ++i_)
; #pragma unroll
;                 for (int e = 0; e < 4; ++e) T[s_ * 4608 + (c4 + e) * 72 + kk0 + 32 * i_] = f2bf(v[s_ * 2 + i_][e]);
;         __syncthreads();
;         const int nx = st + gridDim.x;
;         if (nx < nsuper) CW_LOAD(nx);
.LBB0_30:
	s_waitcnt vmcnt(15)
	v_bfe_u32 v72, v0, 16, 1
	v_add3_u32 v72, v0, v72, s70
	ds_write_b16_d16_hi v71, v72
	v_bfe_u32 v72, v1, 16, 1
	v_add3_u32 v72, v1, v72, s70
	ds_write_b16_d16_hi v71, v72 offset:144
	v_bfe_u32 v72, v2, 16, 1
	v_add3_u32 v72, v2, v72, s70
	ds_write_b16_d16_hi v71, v72 offset:288
	v_bfe_u32 v72, v3, 16, 1
	v_add3_u32 v72, v3, v72, s70
	ds_write_b16_d16_hi v71, v72 offset:432
	s_waitcnt vmcnt(1)
	v_bfe_u32 v72, v56, 16, 1
	v_add3_u32 v72, v56, v72, s70
	ds_write_b16_d16_hi v86, v72 offset:64
	v_bfe_u32 v72, v57, 16, 1
	v_add3_u32 v72, v57, v72, s70
	ds_write_b16_d16_hi v86, v72 offset:208
	v_bfe_u32 v72, v58, 16, 1
	v_add3_u32 v72, v58, v72, s70
	ds_write_b16_d16_hi v86, v72 offset:352
	v_bfe_u32 v72, v59, 16, 1
	v_add3_u32 v72, v59, v72, s70
	ds_write_b16_d16_hi v86, v72 offset:496
	v_bfe_u32 v72, v4, 16, 1
	v_add3_u32 v72, v4, v72, s70
	ds_write_b16_d16_hi v71, v72 offset:9216
	v_bfe_u32 v72, v5, 16, 1
	v_add3_u32 v72, v5, v72, s70
	ds_write_b16_d16_hi v71, v72 offset:9360
	v_bfe_u32 v72, v6, 16, 1
	v_add3_u32 v72, v6, v72, s70
	ds_write_b16_d16_hi v71, v72 offset:9504
	v_bfe_u32 v72, v7, 16, 1
	v_add3_u32 v72, v7, v72, s70
	ds_write_b16_d16_hi v71, v72 offset:9648
	v_bfe_u32 v72, v8, 16, 1
	v_add3_u32 v72, v8, v72, s70
	ds_write_b16_d16_hi v86, v72 offset:9280
	v_bfe_u32 v72, v9, 16, 1
	v_add3_u32 v72, v9, v72, s70
	ds_write_b16_d16_hi v86, v72 offset:9424
	v_bfe_u32 v72, v10, 16, 1
	v_add3_u32 v72, v10, v72, s70
	ds_write_b16_d16_hi v86, v72 offset:9568
	v_bfe_u32 v72, v11, 16, 1
	v_add3_u32 v72, v11, v72, s70
	ds_write_b16_d16_hi v86, v72 offset:9712
	v_bfe_u32 v72, v16, 16, 1
	v_add3_u32 v72, v16, v72, s70
	ds_write_b16_d16_hi v71, v72 offset:18432
	v_bfe_u32 v72, v17, 16, 1
	v_add3_u32 v72, v17, v72, s70
	ds_write_b16_d16_hi v71, v72 offset:18576
	v_bfe_u32 v72, v18, 16, 1
	v_add3_u32 v72, v18, v72, s70
	ds_write_b16_d16_hi v71, v72 offset:18720
	v_bfe_u32 v72, v19, 16, 1
	v_add3_u32 v72, v19, v72, s70
	ds_write_b16_d16_hi v71, v72 offset:18864
	v_bfe_u32 v72, v12, 16, 1
	v_add3_u32 v72, v12, v72, s70
	ds_write_b16_d16_hi v86, v72 offset:18496
	v_bfe_u32 v72, v13, 16, 1
	v_add3_u32 v72, v13, v72, s70
	ds_write_b16_d16_hi v86, v72 offset:18640
	v_bfe_u32 v72, v14, 16, 1
	v_add3_u32 v72, v14, v72, s70
	ds_write_b16_d16_hi v86, v72 offset:18784
	v_bfe_u32 v72, v15, 16, 1
	v_add3_u32 v72, v15, v72, s70
	ds_write_b16_d16_hi v86, v72 offset:18928
	v_bfe_u32 v72, v20, 16, 1
	v_add3_u32 v72, v20, v72, s70
	ds_write_b16_d16_hi v71, v72 offset:27648
	v_bfe_u32 v72, v21, 16, 1
	v_add3_u32 v72, v21, v72, s70
	ds_write_b16_d16_hi v71, v72 offset:27792
	v_bfe_u32 v72, v22, 16, 1
	v_add3_u32 v72, v22, v72, s70
	ds_write_b16_d16_hi v71, v72 offset:27936
	v_bfe_u32 v72, v23, 16, 1
	v_add3_u32 v72, v23, v72, s70
	ds_write_b16_d16_hi v71, v72 offset:28080
	v_bfe_u32 v72, v24, 16, 1
	v_add3_u32 v72, v24, v72, s70
	ds_write_b16_d16_hi v86, v72 offset:27712
	v_bfe_u32 v72, v25, 16, 1
	v_add3_u32 v72, v25, v72, s70
	ds_write_b16_d16_hi v86, v72 offset:27856
	v_bfe_u32 v72, v26, 16, 1
	v_add3_u32 v72, v26, v72, s70
	ds_write_b16_d16_hi v86, v72 offset:28000
	v_bfe_u32 v72, v27, 16, 1
	v_add3_u32 v72, v27, v72, s70
	ds_write_b16_d16_hi v86, v72 offset:28144
	v_bfe_u32 v72, v32, 16, 1
	v_add3_u32 v72, v32, v72, s70
	ds_write_b16_d16_hi v71, v72 offset:36864
	v_bfe_u32 v72, v33, 16, 1
	v_add3_u32 v72, v33, v72, s70
	ds_write_b16_d16_hi v71, v72 offset:37008
	v_bfe_u32 v72, v34, 16, 1
	v_add3_u32 v72, v34, v72, s70
	ds_write_b16_d16_hi v71, v72 offset:37152
	v_bfe_u32 v72, v35, 16, 1
	v_add3_u32 v72, v35, v72, s70
	ds_write_b16_d16_hi v71, v72 offset:37296
	v_bfe_u32 v72, v28, 16, 1
	v_add3_u32 v72, v28, v72, s70
	ds_write_b16_d16_hi v86, v72 offset:36928
	v_bfe_u32 v72, v29, 16, 1
	v_add3_u32 v72, v29, v72, s70
	ds_write_b16_d16_hi v86, v72 offset:37072
	v_bfe_u32 v72, v30, 16, 1
	v_add3_u32 v72, v30, v72, s70
	ds_write_b16_d16_hi v86, v72 offset:37216
	v_bfe_u32 v72, v31, 16, 1
	v_add3_u32 v72, v31, v72, s70
	ds_write_b16_d16_hi v86, v72 offset:37360
	v_bfe_u32 v72, v36, 16, 1
	v_add3_u32 v72, v36, v72, s70
	ds_write_b16_d16_hi v71, v72 offset:46080
	v_bfe_u32 v72, v37, 16, 1
	v_add3_u32 v72, v37, v72, s70
	ds_write_b16_d16_hi v71, v72 offset:46224
	v_bfe_u32 v72, v38, 16, 1
	v_add3_u32 v72, v38, v72, s70
	ds_write_b16_d16_hi v71, v72 offset:46368
	v_bfe_u32 v72, v39, 16, 1
	v_add3_u32 v72, v39, v72, s70
	ds_write_b16_d16_hi v71, v72 offset:46512
	v_bfe_u32 v72, v40, 16, 1
	v_add3_u32 v72, v40, v72, s70
	ds_write_b16_d16_hi v86, v72 offset:46144
	v_bfe_u32 v72, v41, 16, 1
	v_add3_u32 v72, v41, v72, s70
	ds_write_b16_d16_hi v86, v72 offset:46288
	v_bfe_u32 v72, v42, 16, 1
	v_add3_u32 v72, v42, v72, s70
	ds_write_b16_d16_hi v86, v72 offset:46432
	v_bfe_u32 v72, v43, 16, 1
	v_add3_u32 v72, v43, v72, s70
	ds_write_b16_d16_hi v86, v72 offset:46576
	v_bfe_u32 v72, v48, 16, 1
	v_add3_u32 v72, v48, v72, s70
	ds_write_b16_d16_hi v71, v72 offset:55296
	v_bfe_u32 v72, v49, 16, 1
	v_add3_u32 v72, v49, v72, s70
	ds_write_b16_d16_hi v71, v72 offset:55440
	v_bfe_u32 v72, v50, 16, 1
	v_add3_u32 v72, v50, v72, s70
	ds_write_b16_d16_hi v71, v72 offset:55584
	v_bfe_u32 v72, v51, 16, 1
	v_add3_u32 v72, v51, v72, s70
	ds_write_b16_d16_hi v71, v72 offset:55728
	v_bfe_u32 v72, v44, 16, 1
	v_add3_u32 v72, v44, v72, s70
	ds_write_b16_d16_hi v86, v72 offset:55360
	v_bfe_u32 v72, v45, 16, 1
	v_add3_u32 v72, v45, v72, s70
	ds_write_b16_d16_hi v86, v72 offset:55504
	v_bfe_u32 v72, v46, 16, 1
	v_add3_u32 v72, v46, v72, s70
	ds_write_b16_d16_hi v86, v72 offset:55648
	v_bfe_u32 v72, v47, 16, 1
	v_add3_u32 v72, v47, v72, s70
	ds_write_b16_d16_hi v86, v72 offset:55792
	v_bfe_u32 v72, v52, 16, 1
	v_add3_u32 v72, v52, v72, s70
	ds_write_b16_d16_hi v71, v72 offset:64512
	v_bfe_u32 v72, v53, 16, 1
	v_add3_u32 v72, v53, v72, s70
	ds_write_b16_d16_hi v71, v72 offset:64656
	v_bfe_u32 v72, v54, 16, 1
	v_add3_u32 v72, v54, v72, s70
	ds_write_b16_d16_hi v71, v72 offset:64800
	v_bfe_u32 v72, v55, 16, 1
	v_add3_u32 v72, v55, v72, s70
	ds_write_b16_d16_hi v71, v72 offset:64944
	s_waitcnt vmcnt(0)
	v_bfe_u32 v72, v60, 16, 1
	v_add3_u32 v72, v60, v72, s70
	ds_write_b16_d16_hi v86, v72 offset:64576
	v_bfe_u32 v72, v61, 16, 1
	v_add3_u32 v72, v61, v72, s70
	ds_write_b16_d16_hi v86, v72 offset:64720
	v_bfe_u32 v72, v62, 16, 1
	s_add_i32 s9, s8, s80
	v_add3_u32 v72, v62, v72, s70
	s_cmpk_gt_i32 s9, 0x7f
	ds_write_b16_d16_hi v86, v72 offset:64864
	v_bfe_u32 v72, v63, 16, 1
	s_cselect_b64 s[4:5], -1, 0
	v_add3_u32 v72, v63, v72, s70
	s_and_b64 vcc, exec, s[4:5]
	ds_write_b16_d16_hi v86, v72 offset:65008
	s_waitcnt lgkmcnt(0)
	s_barrier
; #define LAS __attribute__((address_space(3)))
; __device__ __forceinline__ bf16_t f2bf(float f) { unsigned u = __float_as_uint(f); u += 0x7FFFu + ((u >> 16) & 1u); return (bf16_t)(u >> 16); }
; __device__ __forceinline__ int fresh_tid() { int t = threadIdx.x; asm volatile("" : "+v"(t)); return t; }
; __device__ __forceinline__ void convert_wt(LAS unsigned char* lds, const float* __restrict__ W, bf16_t* __restrict__ Wt, int K, int N, int mode) {
;     LAS bf16_t* T = (LAS bf16_t*)lds;
;     const int tid = fresh_tid();
;     const int nsn = N / 512, nsuper = (K / 64) * nsn;
;     const int kk0 = tid >> 4, c4 = (tid & 15) * 4;
;     f32x4 v[16];
;     ...
;     int st = blockIdx.x;
;     if (st < nsuper) CW_LOAD(st);
;     for (; st < nsuper; st += gridDim.x) {
;         const int k0 = (st / nsn) * 64, n0 = (st % nsn) * 512;
; #pragma unroll
;         for (int s_ = 0; s_ < 8; ++s_)
; #pragma unroll
;             for (int i_ = 0; i_ < 2; ++i_)
; #pragma unroll
;                 for (int e = 0; e < 4; ++e) T[s_ * 4608 + (c4 + e) * 72 + kk0 + 32 * i_] = f2bf(v[s_ * 2 + i_][e]);
;         __syncthreads();
;         const int nx = st + gridDim.x;
;         if (nx < nsuper) CW_LOAD(nx);
;         { const int n = tid >> 3, k8 = (tid & 7) * 8;
; #pragma unroll
;           for (int s_ = 0; s_ < 8; ++s_) { const u32x4 w = *(const LAS u32x4*)(T + s_ * 4608 + n * 72 + k8);
;               *(u32x4*)(Wt + (size_t)(n0 + s_ * 64 + n) * K + k0 + k8) = w; } }
	s_cbranch_vccnz .LBB0_29
	s_ashr_i32 s10, s9, 31
	s_lshr_b32 s10, s10, 30
	s_add_i32 s10, s9, s10
	s_ashr_i32 s11, s10, 2
	v_readlane_b32 s10, v250, 20
	s_add_i32 s10, s10, s7
	s_lshl_b32 s12, s11, 11
	s_sub_i32 s10, s10, s12
	v_lshl_add_u32 v0, s11, 6, v68
	v_ashrrev_i32_e32 v1, 31, v0
	s_ashr_i32 s11, s10, 31
	v_lshl_add_u64 v[2:3], s[10:11], 2, v[64:65]
	v_lshlrev_b64 v[0:1], 13, v[0:1]
	v_lshl_add_u64 v[52:53], v[2:3], 0, v[0:1]
	s_mov_b64 s[10:11], 0x40000
	v_add_co_u32_e32 v56, vcc, s71, v52
	v_lshl_add_u64 v[60:61], v[52:53], 0, s[10:11]
	s_nop 0
	v_addc_co_u32_e32 v57, vcc, 0, v53, vcc
	global_load_dwordx4 v[0:3], v[52:53], off
	global_load_dwordx4 v[4:7], v[52:53], off offset:256
	global_load_dwordx4 v[8:11], v[60:61], off offset:256
	global_load_dwordx4 v[12:15], v[60:61], off offset:512
	global_load_dwordx4 v[16:19], v[52:53], off offset:512
	global_load_dwordx4 v[20:23], v[52:53], off offset:768
	global_load_dwordx4 v[24:27], v[60:61], off offset:768
	global_load_dwordx4 v[28:31], v[60:61], off offset:1024
	global_load_dwordx4 v[32:35], v[52:53], off offset:1024
	global_load_dwordx4 v[36:39], v[52:53], off offset:1280
	global_load_dwordx4 v[40:43], v[60:61], off offset:1280
	global_load_dwordx4 v[44:47], v[60:61], off offset:1536
	global_load_dwordx4 v[48:51], v[52:53], off offset:1536
	s_nop 0
	global_load_dwordx4 v[52:55], v[52:53], off offset:1792
	s_nop 0
	global_load_dwordx4 v[56:59], v[56:57], off
	s_nop 0
	global_load_dwordx4 v[60:63], v[60:61], off offset:1792
	s_branch .LBB0_29
.LBB0_32:
	v_readlane_b32 s4, v250, 39
	v_readlane_b32 s5, v250, 40
	v_mov_b32_e32 v66, v230
	s_andn2_b64 vcc, exec, s[4:5]
	s_cbranch_vccnz .LBB0_37
	v_readlane_b32 s4, v251, 38
	v_readlane_b32 s8, v251, 22
	s_mul_i32 s4, s4, 0x5800000
	v_readlane_b32 s10, v251, 24
	s_waitcnt vmcnt(23)
	v_lshlrev_b32_e32 v0, 2, v66
	v_readlane_b32 s5, v251, 39
	v_readlane_b32 s11, v251, 25
	s_add_u32 s4, s10, s4
	v_and_b32_e32 v70, 60, v0
	s_addc_u32 s5, s11, 0
	v_lshlrev_b32_e32 v0, 2, v70
	v_mov_b32_e32 v1, v192
	v_ashrrev_i32_e32 v68, 4, v66
	v_readlane_b32 s6, v250, 41
	v_lshl_add_u64 v[64:65], s[4:5], 0, v[0:1]
	v_readlane_b32 s4, v250, 42
	s_waitcnt vmcnt(9)
	v_add_u32_e32 v58, s6, v68
	v_readlane_b32 s5, v250, 43
	s_waitcnt vmcnt(8)
	v_add_u32_e32 v60, 32, v58
	v_ashrrev_i32_e32 v72, 3, v66
	v_lshl_add_u64 v[56:57], s[4:5], 2, v[64:65]
	v_mad_i64_i32 v[36:37], s[4:5], v58, s72, v[56:57]
	v_mad_i64_i32 v[44:45], s[4:5], v60, s72, v[56:57]
	s_mov_b64 s[4:5], 0x5800
	s_nop 0
	v_lshl_add_u64 v[16:17], v[56:57], 0, s[4:5]
	v_mad_i64_i32 v[18:19], s[4:5], v58, s72, v[16:17]
	v_mad_i64_i32 v[20:21], s[4:5], v60, s72, v[16:17]
	s_mov_b64 s[4:5], 0x5900
	s_nop 0
	v_lshl_add_u64 v[24:25], v[56:57], 0, s[4:5]
	v_mad_i64_i32 v[26:27], s[4:5], v58, s72, v[24:25]
	v_mad_i64_i32 v[28:29], s[4:5], v60, s72, v[24:25]
	s_mov_b64 s[4:5], 0x5a00
	s_nop 0
	v_lshl_add_u64 v[48:49], v[56:57], 0, s[4:5]
	global_load_dwordx4 v[0:3], v[36:37], off
	global_load_dwordx4 v[4:7], v[36:37], off offset:256
	global_load_dwordx4 v[8:11], v[44:45], off
	global_load_dwordx4 v[12:15], v[44:45], off offset:256
	s_nop 0
	global_load_dwordx4 v[16:19], v[18:19], off
	s_nop 0
	global_load_dwordx4 v[20:23], v[20:21], off
	s_nop 0
	global_load_dwordx4 v[24:27], v[26:27], off
	s_nop 0
	global_load_dwordx4 v[28:31], v[28:29], off
	s_nop 0
	global_load_dwordx4 v[32:35], v[36:37], off offset:512
	s_nop 0
	global_load_dwordx4 v[36:39], v[36:37], off offset:768
	s_nop 0
	global_load_dwordx4 v[40:43], v[44:45], off offset:512
	s_nop 0
	global_load_dwordx4 v[44:47], v[44:45], off offset:768
	v_mad_i64_i32 v[50:51], s[4:5], v58, s72, v[48:49]
	v_mad_i64_i32 v[52:53], s[4:5], v60, s72, v[48:49]
	s_mov_b64 s[4:5], 0x5b00
	s_nop 0
	v_lshl_add_u64 v[56:57], v[56:57], 0, s[4:5]
	v_mad_i64_i32 v[58:59], s[4:5], v58, s72, v[56:57]
	v_mad_i64_i32 v[60:61], s[4:5], v60, s72, v[56:57]
	global_load_dwordx4 v[48:51], v[50:51], off
	s_nop 0
	global_load_dwordx4 v[52:55], v[52:53], off
	s_nop 0
	global_load_dwordx4 v[56:59], v[58:59], off
	s_nop 0
	global_load_dwordx4 v[60:63], v[60:61], off
	v_lshlrev_b32_e32 v66, 4, v66
	v_mul_lo_u32 v67, v72, s64
	v_and_b32_e32 v66, 0x70, v66
	v_readlane_b32 s4, v253, 60
	v_add3_u32 v69, 0, v67, v66
	v_mov_b32_e32 v67, v192
	v_readlane_b32 s5, v253, 61
	v_lshlrev_b32_e32 v71, 1, v68
	v_mul_u32_u24_e32 v70, 0x90, v70
	v_lshl_add_u64 v[66:67], s[4:5], 0, v[66:67]
	v_readlane_b32 s4, v254, 47
	v_readlane_b32 s9, v251, 23
	v_add3_u32 v70, 0, v71, v70
	v_add_u32_e32 v71, s4, v72
	s_add_i32 s4, s75, s80
	s_lshl_b32 s6, s80, 9
	s_lshl_b32 s7, s4, 8
	s_lshl_b32 s8, s80, 8
	s_mov_b32 s9, s75
	v_readlane_b32 s12, v251, 26
	v_readlane_b32 s13, v251, 27
	v_readlane_b32 s14, v251, 28
	v_readlane_b32 s15, v251, 29
	v_readlane_b32 s16, v251, 30
	v_readlane_b32 s17, v251, 31
	v_readlane_b32 s18, v251, 32
	v_readlane_b32 s19, v251, 33
	v_readlane_b32 s20, v251, 34
	v_readlane_b32 s21, v251, 35
	v_readlane_b32 s22, v251, 36
	v_readlane_b32 s23, v251, 37
	v_lshrrev_b32_e32 v87, 4, v230
	v_and_b32_e32 v88, 3, v230
	v_lshlrev_b32_e32 v88, 3, v88
	v_xor_b32_e32 v88, v87, v88
	v_sub_u32_e32 v88, v88, v87
	v_bfe_u32 v87, v230, 2, 1
	v_lshlrev_b32_e32 v87, 6, v87
	v_lshl_add_u32 v86, v88, 1, v70
	v_add_u32_e32 v70, v86, v87
	v_sub_u32_e32 v86, v86, v87
	v_and_b32_e32 v87, 7, v230
	v_bfe_u32 v88, v230, 5, 3
	v_xor_b32_e32 v88, v87, v88
	v_sub_u32_e32 v88, v88, v87
	v_lshl_add_u32 v69, v88, 4, v69
	s_branch .LBB0_35

; __device__ __forceinline__ bf16_t f2bf(float f) { unsigned u = __float_as_uint(f); u += 0x7FFFu + ((u >> 16) & 1u); return (bf16_t)(u >> 16); }
; __device__ __forceinline__ void convert_wt(LAS unsigned char* lds, const float* __restrict__ W, bf16_t* __restrict__ Wt, int K, int N, int mode) {
;     ...
;     for (; st < nsuper; st += gridDim.x) {
;         const int k0 = (st / nsn) * 64, n0 = (st % nsn) * 512;
; #pragma unroll
;         for (int s_ = 0; s_ < 8; ++s_)
; #pragma unroll
;             for (int i_ = 0; i_ < 2; ++i_)
; #pragma unroll
;                 for (int e = 0; e < 4; ++e) T[s_ * 4608 + (c4 + e) * 72 + kk0 + 32 * i_] = f2bf(v[s_ * 2 + i_][e]);
;         __syncthreads();
;         const int nx = st + gridDim.x;
;         if (nx < nsuper) CW_LOAD(nx);
.LBB0_35:
	s_waitcnt vmcnt(15)
	v_bfe_u32 v72, v0, 16, 1
	v_add3_u32 v72, v0, v72, s70
	ds_write_b16_d16_hi v70, v72
	v_bfe_u32 v72, v1, 16, 1
	v_add3_u32 v72, v1, v72, s70
	ds_write_b16_d16_hi v70, v72 offset:144
	v_bfe_u32 v72, v2, 16, 1
	v_add3_u32 v72, v2, v72, s70
	ds_write_b16_d16_hi v70, v72 offset:288
	v_bfe_u32 v72, v3, 16, 1
	v_add3_u32 v72, v3, v72, s70
	ds_write_b16_d16_hi v70, v72 offset:432
	s_waitcnt vmcnt(13)
	v_bfe_u32 v72, v8, 16, 1
	v_add3_u32 v72, v8, v72, s70
	ds_write_b16_d16_hi v86, v72 offset:64
	v_bfe_u32 v72, v9, 16, 1
	v_add3_u32 v72, v9, v72, s70
	ds_write_b16_d16_hi v86, v72 offset:208
	v_bfe_u32 v72, v10, 16, 1
	v_add3_u32 v72, v10, v72, s70
	ds_write_b16_d16_hi v86, v72 offset:352
	v_bfe_u32 v72, v11, 16, 1
	v_add3_u32 v72, v11, v72, s70
	ds_write_b16_d16_hi v86, v72 offset:496
	v_bfe_u32 v72, v4, 16, 1
	v_add3_u32 v72, v4, v72, s70
	ds_write_b16_d16_hi v70, v72 offset:9216
	v_bfe_u32 v72, v5, 16, 1
	v_add3_u32 v72, v5, v72, s70
	ds_write_b16_d16_hi v70, v72 offset:9360
	v_bfe_u32 v72, v6, 16, 1
	v_add3_u32 v72, v6, v72, s70
	ds_write_b16_d16_hi v70, v72 offset:9504
	v_bfe_u32 v72, v7, 16, 1
	v_add3_u32 v72, v7, v72, s70
	ds_write_b16_d16_hi v70, v72 offset:9648
	s_waitcnt vmcnt(12)
	v_bfe_u32 v72, v12, 16, 1
	v_add3_u32 v72, v12, v72, s70
	ds_write_b16_d16_hi v86, v72 offset:9280
	v_bfe_u32 v72, v13, 16, 1
	v_add3_u32 v72, v13, v72, s70
	ds_write_b16_d16_hi v86, v72 offset:9424
	v_bfe_u32 v72, v14, 16, 1
	v_add3_u32 v72, v14, v72, s70
	ds_write_b16_d16_hi v86, v72 offset:9568
	v_bfe_u32 v72, v15, 16, 1
	v_add3_u32 v72, v15, v72, s70
	ds_write_b16_d16_hi v86, v72 offset:9712
	s_waitcnt vmcnt(11)
	v_bfe_u32 v72, v16, 16, 1
	v_add3_u32 v72, v16, v72, s70
	ds_write_b16_d16_hi v70, v72 offset:18432
	v_bfe_u32 v72, v17, 16, 1
	v_add3_u32 v72, v17, v72, s70
	ds_write_b16_d16_hi v70, v72 offset:18576
	v_bfe_u32 v72, v18, 16, 1
	v_add3_u32 v72, v18, v72, s70
	ds_write_b16_d16_hi v70, v72 offset:18720
	v_bfe_u32 v72, v19, 16, 1
	v_add3_u32 v72, v19, v72, s70
	ds_write_b16_d16_hi v70, v72 offset:18864
	s_waitcnt vmcnt(10)
	v_bfe_u32 v72, v20, 16, 1
	v_add3_u32 v72, v20, v72, s70
	ds_write_b16_d16_hi v86, v72 offset:18496
	v_bfe_u32 v72, v21, 16, 1
	v_add3_u32 v72, v21, v72, s70
	ds_write_b16_d16_hi v86, v72 offset:18640
	v_bfe_u32 v72, v22, 16, 1
	v_add3_u32 v72, v22, v72, s70
	ds_write_b16_d16_hi v86, v72 offset:18784
	v_bfe_u32 v72, v23, 16, 1
	v_add3_u32 v72, v23, v72, s70
	ds_write_b16_d16_hi v86, v72 offset:18928
	s_waitcnt vmcnt(9)
	v_bfe_u32 v72, v24, 16, 1
	v_add3_u32 v72, v24, v72, s70
	ds_write_b16_d16_hi v70, v72 offset:27648
	v_bfe_u32 v72, v25, 16, 1
	v_add3_u32 v72, v25, v72, s70
	ds_write_b16_d16_hi v70, v72 offset:27792
	v_bfe_u32 v72, v26, 16, 1
	v_add3_u32 v72, v26, v72, s70
	ds_write_b16_d16_hi v70, v72 offset:27936
	v_bfe_u32 v72, v27, 16, 1
	v_add3_u32 v72, v27, v72, s70
	ds_write_b16_d16_hi v70, v72 offset:28080
	s_waitcnt vmcnt(8)
	v_bfe_u32 v72, v28, 16, 1
	v_add3_u32 v72, v28, v72, s70
	ds_write_b16_d16_hi v86, v72 offset:27712
	v_bfe_u32 v72, v29, 16, 1
	v_add3_u32 v72, v29, v72, s70
	ds_write_b16_d16_hi v86, v72 offset:27856
	v_bfe_u32 v72, v30, 16, 1
	v_add3_u32 v72, v30, v72, s70
	ds_write_b16_d16_hi v86, v72 offset:28000
	v_bfe_u32 v72, v31, 16, 1
	v_add3_u32 v72, v31, v72, s70
	ds_write_b16_d16_hi v86, v72 offset:28144
	s_waitcnt vmcnt(7)
	v_bfe_u32 v72, v32, 16, 1
	v_add3_u32 v72, v32, v72, s70
	ds_write_b16_d16_hi v70, v72 offset:36864
	v_bfe_u32 v72, v33, 16, 1
	v_add3_u32 v72, v33, v72, s70
	ds_write_b16_d16_hi v70, v72 offset:37008
	v_bfe_u32 v72, v34, 16, 1
	v_add3_u32 v72, v34, v72, s70
	ds_write_b16_d16_hi v70, v72 offset:37152
	v_bfe_u32 v72, v35, 16, 1
	v_add3_u32 v72, v35, v72, s70
	ds_write_b16_d16_hi v70, v72 offset:37296
	s_waitcnt vmcnt(5)
	v_bfe_u32 v72, v40, 16, 1
	v_add3_u32 v72, v40, v72, s70
	ds_write_b16_d16_hi v86, v72 offset:36928
	v_bfe_u32 v72, v41, 16, 1
	v_add3_u32 v72, v41, v72, s70
	ds_write_b16_d16_hi v86, v72 offset:37072
	v_bfe_u32 v72, v42, 16, 1
	v_add3_u32 v72, v42, v72, s70
	ds_write_b16_d16_hi v86, v72 offset:37216
	v_bfe_u32 v72, v43, 16, 1
	v_add3_u32 v72, v43, v72, s70
	ds_write_b16_d16_hi v86, v72 offset:37360
	v_bfe_u32 v72, v36, 16, 1
	v_add3_u32 v72, v36, v72, s70
	ds_write_b16_d16_hi v70, v72 offset:46080
	v_bfe_u32 v72, v37, 16, 1
	v_add3_u32 v72, v37, v72, s70
	ds_write_b16_d16_hi v70, v72 offset:46224
	v_bfe_u32 v72, v38, 16, 1
	v_add3_u32 v72, v38, v72, s70
	ds_write_b16_d16_hi v70, v72 offset:46368
	v_bfe_u32 v72, v39, 16, 1
	v_add3_u32 v72, v39, v72, s70
	ds_write_b16_d16_hi v70, v72 offset:46512
	s_waitcnt vmcnt(4)
	v_bfe_u32 v72, v44, 16, 1
	v_add3_u32 v72, v44, v72, s70
	ds_write_b16_d16_hi v86, v72 offset:46144
	v_bfe_u32 v72, v45, 16, 1
	v_add3_u32 v72, v45, v72, s70
	ds_write_b16_d16_hi v86, v72 offset:46288
	v_bfe_u32 v72, v46, 16, 1
	v_add3_u32 v72, v46, v72, s70
	ds_write_b16_d16_hi v86, v72 offset:46432
	v_bfe_u32 v72, v47, 16, 1
	v_add3_u32 v72, v47, v72, s70
	ds_write_b16_d16_hi v86, v72 offset:46576
	s_waitcnt vmcnt(3)
	v_bfe_u32 v72, v48, 16, 1
	v_add3_u32 v72, v48, v72, s70
	ds_write_b16_d16_hi v70, v72 offset:55296
	v_bfe_u32 v72, v49, 16, 1
	v_add3_u32 v72, v49, v72, s70
	ds_write_b16_d16_hi v70, v72 offset:55440
	v_bfe_u32 v72, v50, 16, 1
	v_add3_u32 v72, v50, v72, s70
	ds_write_b16_d16_hi v70, v72 offset:55584
	v_bfe_u32 v72, v51, 16, 1
	v_add3_u32 v72, v51, v72, s70
	ds_write_b16_d16_hi v70, v72 offset:55728
	s_waitcnt vmcnt(2)
	v_bfe_u32 v72, v52, 16, 1
	v_add3_u32 v72, v52, v72, s70
	ds_write_b16_d16_hi v86, v72 offset:55360
	v_bfe_u32 v72, v53, 16, 1
	v_add3_u32 v72, v53, v72, s70
	ds_write_b16_d16_hi v86, v72 offset:55504
	v_bfe_u32 v72, v54, 16, 1
	v_add3_u32 v72, v54, v72, s70
	ds_write_b16_d16_hi v86, v72 offset:55648
	v_bfe_u32 v72, v55, 16, 1
	v_add3_u32 v72, v55, v72, s70
	ds_write_b16_d16_hi v86, v72 offset:55792
	s_waitcnt vmcnt(1)
	v_bfe_u32 v72, v56, 16, 1
	v_add3_u32 v72, v56, v72, s70
	ds_write_b16_d16_hi v70, v72 offset:64512
	v_bfe_u32 v72, v57, 16, 1
	v_add3_u32 v72, v57, v72, s70
	ds_write_b16_d16_hi v70, v72 offset:64656
	v_bfe_u32 v72, v58, 16, 1
	v_add3_u32 v72, v58, v72, s70
	ds_write_b16_d16_hi v70, v72 offset:64800
	v_bfe_u32 v72, v59, 16, 1
	v_add3_u32 v72, v59, v72, s70
	ds_write_b16_d16_hi v70, v72 offset:64944
	s_waitcnt vmcnt(0)
	v_bfe_u32 v72, v60, 16, 1
	v_add3_u32 v72, v60, v72, s70
	ds_write_b16_d16_hi v86, v72 offset:64576
	v_bfe_u32 v72, v61, 16, 1
	v_add3_u32 v72, v61, v72, s70
	ds_write_b16_d16_hi v86, v72 offset:64720
	v_bfe_u32 v72, v62, 16, 1
	s_add_i32 s10, s9, s80
	v_add3_u32 v72, v62, v72, s70
	s_cmpk_gt_i32 s10, 0x2bf
	ds_write_b16_d16_hi v86, v72 offset:64864
	v_bfe_u32 v72, v63, 16, 1
	s_cselect_b64 s[4:5], -1, 0
	v_add3_u32 v72, v63, v72, s70
	s_and_b64 vcc, exec, s[4:5]
	ds_write_b16_d16_hi v86, v72 offset:65008
	s_waitcnt lgkmcnt(0)
	s_barrier
; #define LAS __attribute__((address_space(3)))
; __device__ __forceinline__ bf16_t f2bf(float f) { unsigned u = __float_as_uint(f); u += 0x7FFFu + ((u >> 16) & 1u); return (bf16_t)(u >> 16); }
; __device__ __forceinline__ int fresh_tid() { int t = threadIdx.x; asm volatile("" : "+v"(t)); return t; }
; __device__ __forceinline__ void convert_wt(LAS unsigned char* lds, const float* __restrict__ W, bf16_t* __restrict__ Wt, int K, int N, int mode) {
;     LAS bf16_t* T = (LAS bf16_t*)lds;
;     const int tid = fresh_tid();
;     const int nsn = N / 512, nsuper = (K / 64) * nsn;
;     const int kk0 = tid >> 4, c4 = (tid & 15) * 4;
;     f32x4 v[16];
;     ...
;     int st = blockIdx.x;
;     if (st < nsuper) CW_LOAD(st);
;     for (; st < nsuper; st += gridDim.x) {
;         const int k0 = (st / nsn) * 64, n0 = (st % nsn) * 512;
; #pragma unroll
;         for (int s_ = 0; s_ < 8; ++s_)
; #pragma unroll
;             for (int i_ = 0; i_ < 2; ++i_)
; #pragma unroll
;                 for (int e = 0; e < 4; ++e) T[s_ * 4608 + (c4 + e) * 72 + kk0 + 32 * i_] = f2bf(v[s_ * 2 + i_][e]);
;         __syncthreads();
;         const int nx = st + gridDim.x;
;         if (nx < nsuper) CW_LOAD(nx);
;         { const int n = tid >> 3, k8 = (tid & 7) * 8;
; #pragma unroll
;           for (int s_ = 0; s_ < 8; ++s_) { const u32x4 w = *(const LAS u32x4*)(T + s_ * 4608 + n * 72 + k8);
;               *(u32x4*)(Wt + (size_t)(n0 + s_ * 64 + n) * K + k0 + k8) = w; } }
	s_cbranch_vccnz .LBB0_34
	s_mul_hi_i32 s11, s10, 0x2e8ba2e9
	s_lshr_b32 s12, s11, 31
	s_ashr_i32 s11, s11, 2
	s_add_i32 s11, s11, s12
	v_lshl_add_u32 v58, s11, 6, v68
	s_mulk_i32 s11, 0xea00
	s_add_i32 s12, s7, s11
	s_ashr_i32 s13, s12, 31
	v_lshl_add_u64 v[56:57], s[12:13], 2, v[64:65]
	v_add_u32_e32 v60, 32, v58
	v_mad_i64_i32 v[36:37], s[12:13], v58, s72, v[56:57]
	v_mad_i64_i32 v[44:45], s[12:13], v60, s72, v[56:57]
	s_mov_b64 s[12:13], 0x5800
	s_nop 0
	v_lshl_add_u64 v[16:17], v[56:57], 0, s[12:13]
	v_mad_i64_i32 v[18:19], s[12:13], v58, s72, v[16:17]
	v_mad_i64_i32 v[20:21], s[12:13], v60, s72, v[16:17]
	s_mov_b64 s[12:13], 0x5900
	s_nop 0
	v_lshl_add_u64 v[24:25], v[56:57], 0, s[12:13]
	v_mad_i64_i32 v[26:27], s[12:13], v58, s72, v[24:25]
	v_mad_i64_i32 v[28:29], s[12:13], v60, s72, v[24:25]
	s_mov_b64 s[12:13], 0x5a00
	s_nop 0
	v_lshl_add_u64 v[48:49], v[56:57], 0, s[12:13]
	global_load_dwordx4 v[0:3], v[36:37], off
	global_load_dwordx4 v[4:7], v[36:37], off offset:256
	global_load_dwordx4 v[8:11], v[44:45], off
	global_load_dwordx4 v[12:15], v[44:45], off offset:256
	s_nop 0
	global_load_dwordx4 v[16:19], v[18:19], off
	s_nop 0
	global_load_dwordx4 v[20:23], v[20:21], off
	s_nop 0
	global_load_dwordx4 v[24:27], v[26:27], off
	s_nop 0
	global_load_dwordx4 v[28:31], v[28:29], off
	s_nop 0
	global_load_dwordx4 v[32:35], v[36:37], off offset:512
	s_nop 0
	global_load_dwordx4 v[36:39], v[36:37], off offset:768
	s_nop 0
	global_load_dwordx4 v[40:43], v[44:45], off offset:512
	s_nop 0
	global_load_dwordx4 v[44:47], v[44:45], off offset:768
	v_mad_i64_i32 v[50:51], s[12:13], v58, s72, v[48:49]
	v_mad_i64_i32 v[52:53], s[12:13], v60, s72, v[48:49]
	s_mov_b64 s[12:13], 0x5b00
	s_nop 0
	v_lshl_add_u64 v[56:57], v[56:57], 0, s[12:13]
	v_mad_i64_i32 v[58:59], s[12:13], v58, s72, v[56:57]
	v_mad_i64_i32 v[60:61], s[12:13], v60, s72, v[56:57]
	global_load_dwordx4 v[48:51], v[50:51], off
	s_nop 0
	global_load_dwordx4 v[52:55], v[52:53], off
	s_nop 0
	global_load_dwordx4 v[56:59], v[58:59], off
	s_nop 0
	global_load_dwordx4 v[60:63], v[60:61], off
	s_branch .LBB0_34
.LBB0_37:
	v_readlane_b32 s4, v250, 44
	v_readlane_b32 s5, v250, 45
	v_mov_b32_e32 v66, v230
	s_andn2_b64 vcc, exec, s[4:5]
	s_cbranch_vccnz .LBB0_42
	v_readlane_b32 s4, v251, 38
	v_readlane_b32 s8, v251, 22
	s_mul_i32 s4, s4, 0x2c00000
	v_readlane_b32 s16, v251, 30
	s_waitcnt vmcnt(23)
	v_lshlrev_b32_e32 v0, 2, v66
	v_readlane_b32 s5, v251, 39
	v_readlane_b32 s17, v251, 31
	s_add_u32 s4, s16, s4
	v_and_b32_e32 v71, 60, v0
	v_ashrrev_i32_e32 v68, 4, v66
	s_addc_u32 s5, s17, 0
	v_readlane_b32 s6, v250, 32
	v_lshlrev_b32_e32 v2, 2, v71
	v_mov_b32_e32 v3, v192
	v_add_u32_e32 v0, s6, v68
	v_lshl_add_u64 v[64:65], s[4:5], 0, v[2:3]
	v_readlane_b32 s4, v250, 33
	v_ashrrev_i32_e32 v1, 31, v0
	v_readlane_b32 s5, v250, 34
	v_lshlrev_b64 v[0:1], 13, v[0:1]
	v_ashrrev_i32_e32 v69, 3, v66
	v_lshl_add_u64 v[2:3], s[4:5], 2, v[64:65]
	s_waitcnt vmcnt(10)
	v_lshl_add_u64 v[52:53], v[2:3], 0, v[0:1]
	s_mov_b64 s[4:5], 0x40000
	s_waitcnt vmcnt(9)
	v_add_co_u32_e32 v56, vcc, s71, v52
	s_waitcnt vmcnt(8)
	v_lshl_add_u64 v[60:61], v[52:53], 0, s[4:5]
	v_addc_co_u32_e32 v57, vcc, 0, v53, vcc
	global_load_dwordx4 v[0:3], v[52:53], off
	global_load_dwordx4 v[4:7], v[52:53], off offset:256
	global_load_dwordx4 v[8:11], v[60:61], off offset:256
	global_load_dwordx4 v[12:15], v[60:61], off offset:512
	global_load_dwordx4 v[16:19], v[52:53], off offset:512
	global_load_dwordx4 v[20:23], v[52:53], off offset:768
	global_load_dwordx4 v[24:27], v[60:61], off offset:768
	global_load_dwordx4 v[28:31], v[60:61], off offset:1024
	global_load_dwordx4 v[32:35], v[52:53], off offset:1024
	global_load_dwordx4 v[36:39], v[52:53], off offset:1280
	global_load_dwordx4 v[40:43], v[60:61], off offset:1280
	global_load_dwordx4 v[44:47], v[60:61], off offset:1536
	global_load_dwordx4 v[48:51], v[52:53], off offset:1536
	s_nop 0
	global_load_dwordx4 v[52:55], v[52:53], off offset:1792
	s_nop 0
	global_load_dwordx4 v[56:59], v[56:57], off
	s_nop 0
	global_load_dwordx4 v[60:63], v[60:61], off offset:1792
	v_lshlrev_b32_e32 v66, 4, v66
	v_mul_lo_u32 v67, v69, s64
	v_and_b32_e32 v66, 0x70, v66
	v_readlane_b32 s4, v254, 34
	v_lshlrev_b32_e32 v72, 1, v68
	v_add3_u32 v70, 0, v67, v66
	v_mov_b32_e32 v67, v192
	v_readlane_b32 s5, v254, 35
	v_mul_u32_u24_e32 v71, 0x90, v71
	s_lshl_b32 s6, s80, 9
	v_lshl_add_u64 v[66:67], s[4:5], 0, v[66:67]
	v_add3_u32 v71, 0, v72, v71
	s_mov_b32 s7, s6
	s_mov_b32 s8, s75
	v_readlane_b32 s9, v251, 23
	v_readlane_b32 s10, v251, 24
	v_readlane_b32 s11, v251, 25
	v_readlane_b32 s12, v251, 26
	v_readlane_b32 s13, v251, 27
	v_readlane_b32 s14, v251, 28
	v_readlane_b32 s15, v251, 29
	v_readlane_b32 s18, v251, 32
	v_readlane_b32 s19, v251, 33
	v_readlane_b32 s20, v251, 34
	v_readlane_b32 s21, v251, 35
	v_readlane_b32 s22, v251, 36
	v_readlane_b32 s23, v251, 37
	v_lshrrev_b32_e32 v87, 4, v230
	v_and_b32_e32 v88, 3, v230
	v_lshlrev_b32_e32 v88, 3, v88
	v_xor_b32_e32 v88, v87, v88
	v_sub_u32_e32 v88, v88, v87
	v_bfe_u32 v87, v230, 2, 1
	v_lshlrev_b32_e32 v87, 6, v87
	v_lshl_add_u32 v86, v88, 1, v71
	v_add_u32_e32 v71, v86, v87
	v_sub_u32_e32 v86, v86, v87
	v_and_b32_e32 v87, 7, v230
	v_bfe_u32 v88, v230, 5, 3
	v_xor_b32_e32 v88, v87, v88
	v_sub_u32_e32 v88, v88, v87
	v_lshl_add_u32 v70, v88, 4, v70
	s_branch .LBB0_40

; __device__ __forceinline__ bf16_t f2bf(float f) { unsigned u = __float_as_uint(f); u += 0x7FFFu + ((u >> 16) & 1u); return (bf16_t)(u >> 16); }
; __device__ __forceinline__ void convert_wt(LAS unsigned char* lds, const float* __restrict__ W, bf16_t* __restrict__ Wt, int K, int N, int mode) {
;     ...
;     for (; st < nsuper; st += gridDim.x) {
;         const int k0 = (st / nsn) * 64, n0 = (st % nsn) * 512;
; #pragma unroll
;         for (int s_ = 0; s_ < 8; ++s_)
; #pragma unroll
;             for (int i_ = 0; i_ < 2; ++i_)
; #pragma unroll
;                 for (int e = 0; e < 4; ++e) T[s_ * 4608 + (c4 + e) * 72 + kk0 + 32 * i_] = f2bf(v[s_ * 2 + i_][e]);
;         __syncthreads();
;         const int nx = st + gridDim.x;
;         if (nx < nsuper) CW_LOAD(nx);
.LBB0_40:
	s_waitcnt vmcnt(15)
	v_bfe_u32 v72, v0, 16, 1
	v_add3_u32 v72, v0, v72, s70
	ds_write_b16_d16_hi v71, v72
	v_bfe_u32 v72, v1, 16, 1
	v_add3_u32 v72, v1, v72, s70
	ds_write_b16_d16_hi v71, v72 offset:144
	v_bfe_u32 v72, v2, 16, 1
	v_add3_u32 v72, v2, v72, s70
	ds_write_b16_d16_hi v71, v72 offset:288
	v_bfe_u32 v72, v3, 16, 1
	v_add3_u32 v72, v3, v72, s70
	ds_write_b16_d16_hi v71, v72 offset:432
	s_waitcnt vmcnt(1)
	v_bfe_u32 v72, v56, 16, 1
	v_add3_u32 v72, v56, v72, s70
	ds_write_b16_d16_hi v86, v72 offset:64
	v_bfe_u32 v72, v57, 16, 1
	v_add3_u32 v72, v57, v72, s70
	ds_write_b16_d16_hi v86, v72 offset:208
	v_bfe_u32 v72, v58, 16, 1
	v_add3_u32 v72, v58, v72, s70
	ds_write_b16_d16_hi v86, v72 offset:352
	v_bfe_u32 v72, v59, 16, 1
	v_add3_u32 v72, v59, v72, s70
	ds_write_b16_d16_hi v86, v72 offset:496
	v_bfe_u32 v72, v4, 16, 1
	v_add3_u32 v72, v4, v72, s70
	ds_write_b16_d16_hi v71, v72 offset:9216
	v_bfe_u32 v72, v5, 16, 1
	v_add3_u32 v72, v5, v72, s70
	ds_write_b16_d16_hi v71, v72 offset:9360
	v_bfe_u32 v72, v6, 16, 1
	v_add3_u32 v72, v6, v72, s70
	ds_write_b16_d16_hi v71, v72 offset:9504
	v_bfe_u32 v72, v7, 16, 1
	v_add3_u32 v72, v7, v72, s70
	ds_write_b16_d16_hi v71, v72 offset:9648
	v_bfe_u32 v72, v8, 16, 1
	v_add3_u32 v72, v8, v72, s70
	ds_write_b16_d16_hi v86, v72 offset:9280
	v_bfe_u32 v72, v9, 16, 1
	v_add3_u32 v72, v9, v72, s70
	ds_write_b16_d16_hi v86, v72 offset:9424
	v_bfe_u32 v72, v10, 16, 1
	v_add3_u32 v72, v10, v72, s70
	ds_write_b16_d16_hi v86, v72 offset:9568
	v_bfe_u32 v72, v11, 16, 1
	v_add3_u32 v72, v11, v72, s70
	ds_write_b16_d16_hi v86, v72 offset:9712
	v_bfe_u32 v72, v16, 16, 1
	v_add3_u32 v72, v16, v72, s70
	ds_write_b16_d16_hi v71, v72 offset:18432
	v_bfe_u32 v72, v17, 16, 1
	v_add3_u32 v72, v17, v72, s70
	ds_write_b16_d16_hi v71, v72 offset:18576
	v_bfe_u32 v72, v18, 16, 1
	v_add3_u32 v72, v18, v72, s70
	ds_write_b16_d16_hi v71, v72 offset:18720
	v_bfe_u32 v72, v19, 16, 1
	v_add3_u32 v72, v19, v72, s70
	ds_write_b16_d16_hi v71, v72 offset:18864
	v_bfe_u32 v72, v12, 16, 1
	v_add3_u32 v72, v12, v72, s70
	ds_write_b16_d16_hi v86, v72 offset:18496
	v_bfe_u32 v72, v13, 16, 1
	v_add3_u32 v72, v13, v72, s70
	ds_write_b16_d16_hi v86, v72 offset:18640
	v_bfe_u32 v72, v14, 16, 1
	v_add3_u32 v72, v14, v72, s70
	ds_write_b16_d16_hi v86, v72 offset:18784
	v_bfe_u32 v72, v15, 16, 1
	v_add3_u32 v72, v15, v72, s70
	ds_write_b16_d16_hi v86, v72 offset:18928
	v_bfe_u32 v72, v20, 16, 1
	v_add3_u32 v72, v20, v72, s70
	ds_write_b16_d16_hi v71, v72 offset:27648
	v_bfe_u32 v72, v21, 16, 1
	v_add3_u32 v72, v21, v72, s70
	ds_write_b16_d16_hi v71, v72 offset:27792
	v_bfe_u32 v72, v22, 16, 1
	v_add3_u32 v72, v22, v72, s70
	ds_write_b16_d16_hi v71, v72 offset:27936
	v_bfe_u32 v72, v23, 16, 1
	v_add3_u32 v72, v23, v72, s70
	ds_write_b16_d16_hi v71, v72 offset:28080
	v_bfe_u32 v72, v24, 16, 1
	v_add3_u32 v72, v24, v72, s70
	ds_write_b16_d16_hi v86, v72 offset:27712
	v_bfe_u32 v72, v25, 16, 1
	v_add3_u32 v72, v25, v72, s70
	ds_write_b16_d16_hi v86, v72 offset:27856
	v_bfe_u32 v72, v26, 16, 1
	v_add3_u32 v72, v26, v72, s70
	ds_write_b16_d16_hi v86, v72 offset:28000
	v_bfe_u32 v72, v27, 16, 1
	v_add3_u32 v72, v27, v72, s70
	ds_write_b16_d16_hi v86, v72 offset:28144
	v_bfe_u32 v72, v32, 16, 1
	v_add3_u32 v72, v32, v72, s70
	ds_write_b16_d16_hi v71, v72 offset:36864
	v_bfe_u32 v72, v33, 16, 1
	v_add3_u32 v72, v33, v72, s70
	ds_write_b16_d16_hi v71, v72 offset:37008
	v_bfe_u32 v72, v34, 16, 1
	v_add3_u32 v72, v34, v72, s70
	ds_write_b16_d16_hi v71, v72 offset:37152
	v_bfe_u32 v72, v35, 16, 1
	v_add3_u32 v72, v35, v72, s70
	ds_write_b16_d16_hi v71, v72 offset:37296
	v_bfe_u32 v72, v28, 16, 1
	v_add3_u32 v72, v28, v72, s70
	ds_write_b16_d16_hi v86, v72 offset:36928
	v_bfe_u32 v72, v29, 16, 1
	v_add3_u32 v72, v29, v72, s70
	ds_write_b16_d16_hi v86, v72 offset:37072
	v_bfe_u32 v72, v30, 16, 1
	v_add3_u32 v72, v30, v72, s70
	ds_write_b16_d16_hi v86, v72 offset:37216
	v_bfe_u32 v72, v31, 16, 1
	v_add3_u32 v72, v31, v72, s70
	ds_write_b16_d16_hi v86, v72 offset:37360
	v_bfe_u32 v72, v36, 16, 1
	v_add3_u32 v72, v36, v72, s70
	ds_write_b16_d16_hi v71, v72 offset:46080
	v_bfe_u32 v72, v37, 16, 1
	v_add3_u32 v72, v37, v72, s70
	ds_write_b16_d16_hi v71, v72 offset:46224
	v_bfe_u32 v72, v38, 16, 1
	v_add3_u32 v72, v38, v72, s70
	ds_write_b16_d16_hi v71, v72 offset:46368
	v_bfe_u32 v72, v39, 16, 1
	v_add3_u32 v72, v39, v72, s70
	ds_write_b16_d16_hi v71, v72 offset:46512
	v_bfe_u32 v72, v40, 16, 1
	v_add3_u32 v72, v40, v72, s70
	ds_write_b16_d16_hi v86, v72 offset:46144
	v_bfe_u32 v72, v41, 16, 1
	v_add3_u32 v72, v41, v72, s70
	ds_write_b16_d16_hi v86, v72 offset:46288
	v_bfe_u32 v72, v42, 16, 1
	v_add3_u32 v72, v42, v72, s70
	ds_write_b16_d16_hi v86, v72 offset:46432
	v_bfe_u32 v72, v43, 16, 1
	v_add3_u32 v72, v43, v72, s70
	ds_write_b16_d16_hi v86, v72 offset:46576
	v_bfe_u32 v72, v48, 16, 1
	v_add3_u32 v72, v48, v72, s70
	ds_write_b16_d16_hi v71, v72 offset:55296
	v_bfe_u32 v72, v49, 16, 1
	v_add3_u32 v72, v49, v72, s70
	ds_write_b16_d16_hi v71, v72 offset:55440
	v_bfe_u32 v72, v50, 16, 1
	v_add3_u32 v72, v50, v72, s70
	ds_write_b16_d16_hi v71, v72 offset:55584
	v_bfe_u32 v72, v51, 16, 1
	v_add3_u32 v72, v51, v72, s70
	ds_write_b16_d16_hi v71, v72 offset:55728
	v_bfe_u32 v72, v44, 16, 1
	v_add3_u32 v72, v44, v72, s70
	ds_write_b16_d16_hi v86, v72 offset:55360
	v_bfe_u32 v72, v45, 16, 1
	v_add3_u32 v72, v45, v72, s70
	ds_write_b16_d16_hi v86, v72 offset:55504
	v_bfe_u32 v72, v46, 16, 1
	v_add3_u32 v72, v46, v72, s70
	ds_write_b16_d16_hi v86, v72 offset:55648
	v_bfe_u32 v72, v47, 16, 1
	v_add3_u32 v72, v47, v72, s70
	ds_write_b16_d16_hi v86, v72 offset:55792
	v_bfe_u32 v72, v52, 16, 1
	v_add3_u32 v72, v52, v72, s70
	ds_write_b16_d16_hi v71, v72 offset:64512
	v_bfe_u32 v72, v53, 16, 1
	v_add3_u32 v72, v53, v72, s70
	ds_write_b16_d16_hi v71, v72 offset:64656
	v_bfe_u32 v72, v54, 16, 1
	v_add3_u32 v72, v54, v72, s70
	ds_write_b16_d16_hi v71, v72 offset:64800
	v_bfe_u32 v72, v55, 16, 1
	v_add3_u32 v72, v55, v72, s70
	ds_write_b16_d16_hi v71, v72 offset:64944
	s_waitcnt vmcnt(0)
	v_bfe_u32 v72, v60, 16, 1
	v_add3_u32 v72, v60, v72, s70
	ds_write_b16_d16_hi v86, v72 offset:64576
	v_bfe_u32 v72, v61, 16, 1
	v_add3_u32 v72, v61, v72, s70
	ds_write_b16_d16_hi v86, v72 offset:64720
	v_bfe_u32 v72, v62, 16, 1
	s_add_i32 s9, s8, s80
	v_add3_u32 v72, v62, v72, s70
	s_cmpk_gt_i32 s9, 0x15f
	ds_write_b16_d16_hi v86, v72 offset:64864
	v_bfe_u32 v72, v63, 16, 1
	s_cselect_b64 s[4:5], -1, 0
	v_add3_u32 v72, v63, v72, s70
	s_and_b64 vcc, exec, s[4:5]
	ds_write_b16_d16_hi v86, v72 offset:65008
	s_waitcnt lgkmcnt(0)
	s_barrier
; #define LAS __attribute__((address_space(3)))
; __device__ __forceinline__ bf16_t f2bf(float f) { unsigned u = __float_as_uint(f); u += 0x7FFFu + ((u >> 16) & 1u); return (bf16_t)(u >> 16); }
; __device__ __forceinline__ int fresh_tid() { int t = threadIdx.x; asm volatile("" : "+v"(t)); return t; }
; __device__ __forceinline__ void convert_wt(LAS unsigned char* lds, const float* __restrict__ W, bf16_t* __restrict__ Wt, int K, int N, int mode) {
;     LAS bf16_t* T = (LAS bf16_t*)lds;
;     const int tid = fresh_tid();
;     const int nsn = N / 512, nsuper = (K / 64) * nsn;
;     const int kk0 = tid >> 4, c4 = (tid & 15) * 4;
;     f32x4 v[16];
;     ...
;     int st = blockIdx.x;
;     if (st < nsuper) CW_LOAD(st);
;     for (; st < nsuper; st += gridDim.x) {
;         const int k0 = (st / nsn) * 64, n0 = (st % nsn) * 512;
; #pragma unroll
;         for (int s_ = 0; s_ < 8; ++s_)
; #pragma unroll
;             for (int i_ = 0; i_ < 2; ++i_)
; #pragma unroll
;                 for (int e = 0; e < 4; ++e) T[s_ * 4608 + (c4 + e) * 72 + kk0 + 32 * i_] = f2bf(v[s_ * 2 + i_][e]);
;         __syncthreads();
;         const int nx = st + gridDim.x;
;         if (nx < nsuper) CW_LOAD(nx);
;         { const int n = tid >> 3, k8 = (tid & 7) * 8;
; #pragma unroll
;           for (int s_ = 0; s_ < 8; ++s_) { const u32x4 w = *(const LAS u32x4*)(T + s_ * 4608 + n * 72 + k8);
;               *(u32x4*)(Wt + (size_t)(n0 + s_ * 64 + n) * K + k0 + k8) = w; } }
	s_cbranch_vccnz .LBB0_39
	s_ashr_i32 s10, s9, 31
	s_lshr_b32 s10, s10, 30
	s_add_i32 s10, s9, s10
	s_ashr_i32 s11, s10, 2
	v_readlane_b32 s10, v250, 20
	s_add_i32 s10, s10, s7
	s_lshl_b32 s12, s11, 11
	s_sub_i32 s10, s10, s12
	v_lshl_add_u32 v0, s11, 6, v68
	v_ashrrev_i32_e32 v1, 31, v0
	s_ashr_i32 s11, s10, 31
	v_lshl_add_u64 v[2:3], s[10:11], 2, v[64:65]
	v_lshlrev_b64 v[0:1], 13, v[0:1]
	v_lshl_add_u64 v[52:53], v[2:3], 0, v[0:1]
	s_mov_b64 s[10:11], 0x40000
	v_add_co_u32_e32 v56, vcc, s71, v52
	v_lshl_add_u64 v[60:61], v[52:53], 0, s[10:11]
	s_nop 0
	v_addc_co_u32_e32 v57, vcc, 0, v53, vcc
	global_load_dwordx4 v[0:3], v[52:53], off
	global_load_dwordx4 v[4:7], v[52:53], off offset:256
	global_load_dwordx4 v[8:11], v[60:61], off offset:256
	global_load_dwordx4 v[12:15], v[60:61], off offset:512
	global_load_dwordx4 v[16:19], v[52:53], off offset:512
	global_load_dwordx4 v[20:23], v[52:53], off offset:768
	global_load_dwordx4 v[24:27], v[60:61], off offset:768
	global_load_dwordx4 v[28:31], v[60:61], off offset:1024
	global_load_dwordx4 v[32:35], v[52:53], off offset:1024
	global_load_dwordx4 v[36:39], v[52:53], off offset:1280
	global_load_dwordx4 v[40:43], v[60:61], off offset:1280
	global_load_dwordx4 v[44:47], v[60:61], off offset:1536
	global_load_dwordx4 v[48:51], v[52:53], off offset:1536
	s_nop 0
	global_load_dwordx4 v[52:55], v[52:53], off offset:1792
	s_nop 0
	global_load_dwordx4 v[56:59], v[56:57], off
	s_nop 0
	global_load_dwordx4 v[60:63], v[60:61], off offset:1792
	s_branch .LBB0_39
.LBB0_42:
	v_readlane_b32 s4, v250, 46
	v_readlane_b32 s5, v250, 47
	v_mov_b32_e32 v66, v230
	s_andn2_b64 vcc, exec, s[4:5]
	s_cbranch_vccnz .LBB0_47
	v_readlane_b32 s4, v251, 38
	v_readlane_b32 s5, v251, 39
	v_readlane_b32 s8, v251, 22
	s_lshl_b64 s[4:5], s[4:5], 21
	v_readlane_b32 s20, v251, 34
	s_waitcnt vmcnt(23)
	v_lshlrev_b32_e32 v0, 2, v66
	v_readlane_b32 s21, v251, 35
	s_add_u32 s4, s20, s4
	v_and_b32_e32 v71, 60, v0
	v_ashrrev_i32_e32 v68, 4, v66
	s_addc_u32 s5, s21, s5
	v_readlane_b32 s6, v250, 32
	v_lshlrev_b32_e32 v2, 2, v71
	v_mov_b32_e32 v3, v192
	v_add_u32_e32 v0, s6, v68
	v_lshl_add_u64 v[64:65], s[4:5], 0, v[2:3]
	v_readlane_b32 s4, v250, 33
	v_ashrrev_i32_e32 v1, 31, v0
	v_readlane_b32 s5, v250, 34
	v_lshlrev_b64 v[0:1], 13, v[0:1]
	v_ashrrev_i32_e32 v69, 3, v66
	v_lshl_add_u64 v[2:3], s[4:5], 2, v[64:65]
	s_waitcnt vmcnt(10)
	v_lshl_add_u64 v[52:53], v[2:3], 0, v[0:1]
	s_mov_b64 s[4:5], 0x40000
	s_waitcnt vmcnt(9)
	v_add_co_u32_e32 v56, vcc, s71, v52
	s_waitcnt vmcnt(8)
	v_lshl_add_u64 v[60:61], v[52:53], 0, s[4:5]
	v_addc_co_u32_e32 v57, vcc, 0, v53, vcc
	global_load_dwordx4 v[0:3], v[52:53], off
	global_load_dwordx4 v[4:7], v[52:53], off offset:256
	global_load_dwordx4 v[8:11], v[60:61], off offset:256
	global_load_dwordx4 v[12:15], v[60:61], off offset:512
	global_load_dwordx4 v[16:19], v[52:53], off offset:512
	global_load_dwordx4 v[20:23], v[52:53], off offset:768
	global_load_dwordx4 v[24:27], v[60:61], off offset:768
	global_load_dwordx4 v[28:31], v[60:61], off offset:1024
	global_load_dwordx4 v[32:35], v[52:53], off offset:1024
	global_load_dwordx4 v[36:39], v[52:53], off offset:1280
	global_load_dwordx4 v[40:43], v[60:61], off offset:1280
	global_load_dwordx4 v[44:47], v[60:61], off offset:1536
	global_load_dwordx4 v[48:51], v[52:53], off offset:1536
	s_nop 0
	global_load_dwordx4 v[52:55], v[52:53], off offset:1792
	s_nop 0
	global_load_dwordx4 v[56:59], v[56:57], off
	s_nop 0
	global_load_dwordx4 v[60:63], v[60:61], off offset:1792
	v_lshlrev_b32_e32 v66, 4, v66
	v_mul_lo_u32 v67, v69, s64
	v_and_b32_e32 v66, 0x70, v66
	v_readlane_b32 s4, v254, 10
	v_lshlrev_b32_e32 v72, 1, v68
	v_add3_u32 v70, 0, v67, v66
	v_mov_b32_e32 v67, v192
	v_readlane_b32 s5, v254, 11
	v_mul_u32_u24_e32 v71, 0x90, v71
	s_lshl_b32 s6, s80, 9
	v_lshl_add_u64 v[66:67], s[4:5], 0, v[66:67]
	v_add3_u32 v71, 0, v72, v71
	s_mov_b32 s7, s6
	s_mov_b32 s8, s75
	v_readlane_b32 s9, v251, 23
	v_readlane_b32 s10, v251, 24
	v_readlane_b32 s11, v251, 25
	v_readlane_b32 s12, v251, 26
	v_readlane_b32 s13, v251, 27
	v_readlane_b32 s14, v251, 28
	v_readlane_b32 s15, v251, 29
	v_readlane_b32 s16, v251, 30
	v_readlane_b32 s17, v251, 31
	v_readlane_b32 s18, v251, 32
	v_readlane_b32 s19, v251, 33
	v_readlane_b32 s22, v251, 36
	v_readlane_b32 s23, v251, 37
	v_lshrrev_b32_e32 v87, 4, v230
	v_and_b32_e32 v88, 3, v230
	v_lshlrev_b32_e32 v88, 3, v88
	v_xor_b32_e32 v88, v87, v88
	v_sub_u32_e32 v88, v88, v87
	v_bfe_u32 v87, v230, 2, 1
	v_lshlrev_b32_e32 v87, 6, v87
	v_lshl_add_u32 v86, v88, 1, v71
	v_add_u32_e32 v71, v86, v87
	v_sub_u32_e32 v86, v86, v87
	v_and_b32_e32 v87, 7, v230
	v_bfe_u32 v88, v230, 5, 3
	v_xor_b32_e32 v88, v87, v88
	v_sub_u32_e32 v88, v88, v87
	v_lshl_add_u32 v70, v88, 4, v70
	s_branch .LBB0_45

; __device__ __forceinline__ bf16_t f2bf(float f) { unsigned u = __float_as_uint(f); u += 0x7FFFu + ((u >> 16) & 1u); return (bf16_t)(u >> 16); }
; __device__ __forceinline__ void convert_wt(LAS unsigned char* lds, const float* __restrict__ W, bf16_t* __restrict__ Wt, int K, int N, int mode) {
;     ...
;     for (; st < nsuper; st += gridDim.x) {
;         const int k0 = (st / nsn) * 64, n0 = (st % nsn) * 512;
; #pragma unroll
;         for (int s_ = 0; s_ < 8; ++s_)
; #pragma unroll
;             for (int i_ = 0; i_ < 2; ++i_)
; #pragma unroll
;                 for (int e = 0; e < 4; ++e) T[s_ * 4608 + (c4 + e) * 72 + kk0 + 32 * i_] = f2bf(v[s_ * 2 + i_][e]);
;         __syncthreads();
;         const int nx = st + gridDim.x;
;         if (nx < nsuper) CW_LOAD(nx);
.LBB0_45:
	s_waitcnt vmcnt(15)
	v_bfe_u32 v72, v0, 16, 1
	v_add3_u32 v72, v0, v72, s70
	ds_write_b16_d16_hi v71, v72
	v_bfe_u32 v72, v1, 16, 1
	v_add3_u32 v72, v1, v72, s70
	ds_write_b16_d16_hi v71, v72 offset:144
	v_bfe_u32 v72, v2, 16, 1
	v_add3_u32 v72, v2, v72, s70
	ds_write_b16_d16_hi v71, v72 offset:288
	v_bfe_u32 v72, v3, 16, 1
	v_add3_u32 v72, v3, v72, s70
	ds_write_b16_d16_hi v71, v72 offset:432
	s_waitcnt vmcnt(1)
	v_bfe_u32 v72, v56, 16, 1
	v_add3_u32 v72, v56, v72, s70
	ds_write_b16_d16_hi v86, v72 offset:64
	v_bfe_u32 v72, v57, 16, 1
	v_add3_u32 v72, v57, v72, s70
	ds_write_b16_d16_hi v86, v72 offset:208
	v_bfe_u32 v72, v58, 16, 1
	v_add3_u32 v72, v58, v72, s70
	ds_write_b16_d16_hi v86, v72 offset:352
	v_bfe_u32 v72, v59, 16, 1
	v_add3_u32 v72, v59, v72, s70
	ds_write_b16_d16_hi v86, v72 offset:496
	v_bfe_u32 v72, v4, 16, 1
	v_add3_u32 v72, v4, v72, s70
	ds_write_b16_d16_hi v71, v72 offset:9216
	v_bfe_u32 v72, v5, 16, 1
	v_add3_u32 v72, v5, v72, s70
	ds_write_b16_d16_hi v71, v72 offset:9360
	v_bfe_u32 v72, v6, 16, 1
	v_add3_u32 v72, v6, v72, s70
	ds_write_b16_d16_hi v71, v72 offset:9504
	v_bfe_u32 v72, v7, 16, 1
	v_add3_u32 v72, v7, v72, s70
	ds_write_b16_d16_hi v71, v72 offset:9648
	v_bfe_u32 v72, v8, 16, 1
	v_add3_u32 v72, v8, v72, s70
	ds_write_b16_d16_hi v86, v72 offset:9280
	v_bfe_u32 v72, v9, 16, 1
	v_add3_u32 v72, v9, v72, s70
	ds_write_b16_d16_hi v86, v72 offset:9424
	v_bfe_u32 v72, v10, 16, 1
	v_add3_u32 v72, v10, v72, s70
	ds_write_b16_d16_hi v86, v72 offset:9568
	v_bfe_u32 v72, v11, 16, 1
	v_add3_u32 v72, v11, v72, s70
	ds_write_b16_d16_hi v86, v72 offset:9712
	v_bfe_u32 v72, v16, 16, 1
	v_add3_u32 v72, v16, v72, s70
	ds_write_b16_d16_hi v71, v72 offset:18432
	v_bfe_u32 v72, v17, 16, 1
	v_add3_u32 v72, v17, v72, s70
	ds_write_b16_d16_hi v71, v72 offset:18576
	v_bfe_u32 v72, v18, 16, 1
	v_add3_u32 v72, v18, v72, s70
	ds_write_b16_d16_hi v71, v72 offset:18720
	v_bfe_u32 v72, v19, 16, 1
	v_add3_u32 v72, v19, v72, s70
	ds_write_b16_d16_hi v71, v72 offset:18864
	v_bfe_u32 v72, v12, 16, 1
	v_add3_u32 v72, v12, v72, s70
	ds_write_b16_d16_hi v86, v72 offset:18496
	v_bfe_u32 v72, v13, 16, 1
	v_add3_u32 v72, v13, v72, s70
	ds_write_b16_d16_hi v86, v72 offset:18640
	v_bfe_u32 v72, v14, 16, 1
	v_add3_u32 v72, v14, v72, s70
	ds_write_b16_d16_hi v86, v72 offset:18784
	v_bfe_u32 v72, v15, 16, 1
	v_add3_u32 v72, v15, v72, s70
	ds_write_b16_d16_hi v86, v72 offset:18928
	v_bfe_u32 v72, v20, 16, 1
	v_add3_u32 v72, v20, v72, s70
	ds_write_b16_d16_hi v71, v72 offset:27648
	v_bfe_u32 v72, v21, 16, 1
	v_add3_u32 v72, v21, v72, s70
	ds_write_b16_d16_hi v71, v72 offset:27792
	v_bfe_u32 v72, v22, 16, 1
	v_add3_u32 v72, v22, v72, s70
	ds_write_b16_d16_hi v71, v72 offset:27936
	v_bfe_u32 v72, v23, 16, 1
	v_add3_u32 v72, v23, v72, s70
	ds_write_b16_d16_hi v71, v72 offset:28080
	v_bfe_u32 v72, v24, 16, 1
	v_add3_u32 v72, v24, v72, s70
	ds_write_b16_d16_hi v86, v72 offset:27712
	v_bfe_u32 v72, v25, 16, 1
	v_add3_u32 v72, v25, v72, s70
	ds_write_b16_d16_hi v86, v72 offset:27856
	v_bfe_u32 v72, v26, 16, 1
	v_add3_u32 v72, v26, v72, s70
	ds_write_b16_d16_hi v86, v72 offset:28000
	v_bfe_u32 v72, v27, 16, 1
	v_add3_u32 v72, v27, v72, s70
	ds_write_b16_d16_hi v86, v72 offset:28144
	v_bfe_u32 v72, v32, 16, 1
	v_add3_u32 v72, v32, v72, s70
	ds_write_b16_d16_hi v71, v72 offset:36864
	v_bfe_u32 v72, v33, 16, 1
	v_add3_u32 v72, v33, v72, s70
	ds_write_b16_d16_hi v71, v72 offset:37008
	v_bfe_u32 v72, v34, 16, 1
	v_add3_u32 v72, v34, v72, s70
	ds_write_b16_d16_hi v71, v72 offset:37152
	v_bfe_u32 v72, v35, 16, 1
	v_add3_u32 v72, v35, v72, s70
	ds_write_b16_d16_hi v71, v72 offset:37296
	v_bfe_u32 v72, v28, 16, 1
	v_add3_u32 v72, v28, v72, s70
	ds_write_b16_d16_hi v86, v72 offset:36928
	v_bfe_u32 v72, v29, 16, 1
	v_add3_u32 v72, v29, v72, s70
	ds_write_b16_d16_hi v86, v72 offset:37072
	v_bfe_u32 v72, v30, 16, 1
	v_add3_u32 v72, v30, v72, s70
	ds_write_b16_d16_hi v86, v72 offset:37216
	v_bfe_u32 v72, v31, 16, 1
	v_add3_u32 v72, v31, v72, s70
	ds_write_b16_d16_hi v86, v72 offset:37360
	v_bfe_u32 v72, v36, 16, 1
	v_add3_u32 v72, v36, v72, s70
	ds_write_b16_d16_hi v71, v72 offset:46080
	v_bfe_u32 v72, v37, 16, 1
	v_add3_u32 v72, v37, v72, s70
	ds_write_b16_d16_hi v71, v72 offset:46224
	v_bfe_u32 v72, v38, 16, 1
	v_add3_u32 v72, v38, v72, s70
	ds_write_b16_d16_hi v71, v72 offset:46368
	v_bfe_u32 v72, v39, 16, 1
	v_add3_u32 v72, v39, v72, s70
	ds_write_b16_d16_hi v71, v72 offset:46512
	v_bfe_u32 v72, v40, 16, 1
	v_add3_u32 v72, v40, v72, s70
	ds_write_b16_d16_hi v86, v72 offset:46144
	v_bfe_u32 v72, v41, 16, 1
	v_add3_u32 v72, v41, v72, s70
	ds_write_b16_d16_hi v86, v72 offset:46288
	v_bfe_u32 v72, v42, 16, 1
	v_add3_u32 v72, v42, v72, s70
	ds_write_b16_d16_hi v86, v72 offset:46432
	v_bfe_u32 v72, v43, 16, 1
	v_add3_u32 v72, v43, v72, s70
	ds_write_b16_d16_hi v86, v72 offset:46576
	v_bfe_u32 v72, v48, 16, 1
	v_add3_u32 v72, v48, v72, s70
	ds_write_b16_d16_hi v71, v72 offset:55296
	v_bfe_u32 v72, v49, 16, 1
	v_add3_u32 v72, v49, v72, s70
	ds_write_b16_d16_hi v71, v72 offset:55440
	v_bfe_u32 v72, v50, 16, 1
	v_add3_u32 v72, v50, v72, s70
	ds_write_b16_d16_hi v71, v72 offset:55584
	v_bfe_u32 v72, v51, 16, 1
	v_add3_u32 v72, v51, v72, s70
	ds_write_b16_d16_hi v71, v72 offset:55728
	v_bfe_u32 v72, v44, 16, 1
	v_add3_u32 v72, v44, v72, s70
	ds_write_b16_d16_hi v86, v72 offset:55360
	v_bfe_u32 v72, v45, 16, 1
	v_add3_u32 v72, v45, v72, s70
	ds_write_b16_d16_hi v86, v72 offset:55504
	v_bfe_u32 v72, v46, 16, 1
	v_add3_u32 v72, v46, v72, s70
	ds_write_b16_d16_hi v86, v72 offset:55648
	v_bfe_u32 v72, v47, 16, 1
	v_add3_u32 v72, v47, v72, s70
	ds_write_b16_d16_hi v86, v72 offset:55792
	v_bfe_u32 v72, v52, 16, 1
	v_add3_u32 v72, v52, v72, s70
	ds_write_b16_d16_hi v71, v72 offset:64512
	v_bfe_u32 v72, v53, 16, 1
	v_add3_u32 v72, v53, v72, s70
	ds_write_b16_d16_hi v71, v72 offset:64656
	v_bfe_u32 v72, v54, 16, 1
	v_add3_u32 v72, v54, v72, s70
	ds_write_b16_d16_hi v71, v72 offset:64800
	v_bfe_u32 v72, v55, 16, 1
	v_add3_u32 v72, v55, v72, s70
	ds_write_b16_d16_hi v71, v72 offset:64944
	s_waitcnt vmcnt(0)
	v_bfe_u32 v72, v60, 16, 1
	v_add3_u32 v72, v60, v72, s70
	ds_write_b16_d16_hi v86, v72 offset:64576
	v_bfe_u32 v72, v61, 16, 1
	v_add3_u32 v72, v61, v72, s70
	ds_write_b16_d16_hi v86, v72 offset:64720
	v_bfe_u32 v72, v62, 16, 1
	s_add_i32 s9, s8, s80
	v_add3_u32 v72, v62, v72, s70
	s_cmp_gt_i32 s9, 15
	ds_write_b16_d16_hi v86, v72 offset:64864
	v_bfe_u32 v72, v63, 16, 1
	s_cselect_b64 s[4:5], -1, 0
	v_add3_u32 v72, v63, v72, s70
	s_and_b64 vcc, exec, s[4:5]
	ds_write_b16_d16_hi v86, v72 offset:65008
	s_waitcnt lgkmcnt(0)
	s_barrier
; #define LAS __attribute__((address_space(3)))
; __device__ __forceinline__ bf16_t f2bf(float f) { unsigned u = __float_as_uint(f); u += 0x7FFFu + ((u >> 16) & 1u); return (bf16_t)(u >> 16); }
; __device__ __forceinline__ int fresh_tid() { int t = threadIdx.x; asm volatile("" : "+v"(t)); return t; }
; __device__ __forceinline__ void convert_wt(LAS unsigned char* lds, const float* __restrict__ W, bf16_t* __restrict__ Wt, int K, int N, int mode) {
;     LAS bf16_t* T = (LAS bf16_t*)lds;
;     const int tid = fresh_tid();
;     const int nsn = N / 512, nsuper = (K / 64) * nsn;
;     const int kk0 = tid >> 4, c4 = (tid & 15) * 4;
;     f32x4 v[16];
;     ...
;     int st = blockIdx.x;
;     if (st < nsuper) CW_LOAD(st);
;     for (; st < nsuper; st += gridDim.x) {
;         const int k0 = (st / nsn) * 64, n0 = (st % nsn) * 512;
; #pragma unroll
;         for (int s_ = 0; s_ < 8; ++s_)
; #pragma unroll
;             for (int i_ = 0; i_ < 2; ++i_)
; #pragma unroll
;                 for (int e = 0; e < 4; ++e) T[s_ * 4608 + (c4 + e) * 72 + kk0 + 32 * i_] = f2bf(v[s_ * 2 + i_][e]);
;         __syncthreads();
;         const int nx = st + gridDim.x;
;         if (nx < nsuper) CW_LOAD(nx);
;         { const int n = tid >> 3, k8 = (tid & 7) * 8;
; #pragma unroll
;           for (int s_ = 0; s_ < 8; ++s_) { const u32x4 w = *(const LAS u32x4*)(T + s_ * 4608 + n * 72 + k8);
;               *(u32x4*)(Wt + (size_t)(n0 + s_ * 64 + n) * K + k0 + k8) = w; } }
	s_cbranch_vccnz .LBB0_44
	s_ashr_i32 s10, s9, 31
	s_lshr_b32 s10, s10, 30
	s_add_i32 s10, s9, s10
	s_ashr_i32 s11, s10, 2
	v_readlane_b32 s10, v250, 20
	s_add_i32 s10, s10, s7
	s_lshl_b32 s12, s11, 11
	s_sub_i32 s10, s10, s12
	v_lshl_add_u32 v0, s11, 6, v68
	v_ashrrev_i32_e32 v1, 31, v0
	s_ashr_i32 s11, s10, 31
	v_lshl_add_u64 v[2:3], s[10:11], 2, v[64:65]
	v_lshlrev_b64 v[0:1], 13, v[0:1]
	v_lshl_add_u64 v[52:53], v[2:3], 0, v[0:1]
	s_mov_b64 s[10:11], 0x40000
	v_add_co_u32_e32 v56, vcc, s71, v52
	v_lshl_add_u64 v[60:61], v[52:53], 0, s[10:11]
	s_nop 0
	v_addc_co_u32_e32 v57, vcc, 0, v53, vcc
	global_load_dwordx4 v[0:3], v[52:53], off
	global_load_dwordx4 v[4:7], v[52:53], off offset:256
	global_load_dwordx4 v[8:11], v[60:61], off offset:256
	global_load_dwordx4 v[12:15], v[60:61], off offset:512
	global_load_dwordx4 v[16:19], v[52:53], off offset:512
	global_load_dwordx4 v[20:23], v[52:53], off offset:768
	global_load_dwordx4 v[24:27], v[60:61], off offset:768
	global_load_dwordx4 v[28:31], v[60:61], off offset:1024
	global_load_dwordx4 v[32:35], v[52:53], off offset:1024
	global_load_dwordx4 v[36:39], v[52:53], off offset:1280
	global_load_dwordx4 v[40:43], v[60:61], off offset:1280
	global_load_dwordx4 v[44:47], v[60:61], off offset:1536
	global_load_dwordx4 v[48:51], v[52:53], off offset:1536
	s_nop 0
	global_load_dwordx4 v[52:55], v[52:53], off offset:1792
	s_nop 0
	global_load_dwordx4 v[56:59], v[56:57], off
	s_nop 0
	global_load_dwordx4 v[60:63], v[60:61], off offset:1792
	s_branch .LBB0_44
.LBB0_47:
	v_mov_b32_e32 v66, v230
	s_and_b64 vcc, exec, s[38:39]
	s_cbranch_vccnz .LBB0_52
	v_readlane_b32 s4, v251, 22
	s_lshl_b64 s[0:1], s[0:1], 2
	v_readlane_b32 s18, v251, 36
	s_waitcnt vmcnt(23)
	v_lshlrev_b32_e32 v0, 2, v66
	v_readlane_b32 s19, v251, 37
	s_add_u32 s0, s18, s0
	v_and_b32_e32 v71, 60, v0
	v_ashrrev_i32_e32 v68, 4, v66
	s_addc_u32 s1, s19, s1
	v_readlane_b32 s4, v250, 32
	v_lshlrev_b32_e32 v2, 2, v71
	v_mov_b32_e32 v3, v192
	v_add_u32_e32 v0, s4, v68
	v_lshl_add_u64 v[64:65], s[0:1], 0, v[2:3]
	v_readlane_b32 s0, v250, 33
	v_ashrrev_i32_e32 v1, 31, v0
	v_readlane_b32 s1, v250, 34
	v_lshlrev_b64 v[0:1], 13, v[0:1]
	v_ashrrev_i32_e32 v69, 3, v66
	v_lshl_add_u64 v[2:3], s[0:1], 2, v[64:65]
	s_waitcnt vmcnt(10)
	v_lshl_add_u64 v[52:53], v[2:3], 0, v[0:1]
	s_mov_b64 s[0:1], 0x40000
	s_waitcnt vmcnt(9)
	v_add_co_u32_e32 v56, vcc, s71, v52
	s_waitcnt vmcnt(8)
	v_lshl_add_u64 v[60:61], v[52:53], 0, s[0:1]
	v_addc_co_u32_e32 v57, vcc, 0, v53, vcc
	global_load_dwordx4 v[0:3], v[52:53], off
	global_load_dwordx4 v[4:7], v[52:53], off offset:256
	global_load_dwordx4 v[8:11], v[60:61], off offset:256
	global_load_dwordx4 v[12:15], v[60:61], off offset:512
	global_load_dwordx4 v[16:19], v[52:53], off offset:512
	global_load_dwordx4 v[20:23], v[52:53], off offset:768
	global_load_dwordx4 v[24:27], v[60:61], off offset:768
	global_load_dwordx4 v[28:31], v[60:61], off offset:1024
	global_load_dwordx4 v[32:35], v[52:53], off offset:1024
	global_load_dwordx4 v[36:39], v[52:53], off offset:1280
	global_load_dwordx4 v[40:43], v[60:61], off offset:1280
	global_load_dwordx4 v[44:47], v[60:61], off offset:1536
	global_load_dwordx4 v[48:51], v[52:53], off offset:1536
	s_nop 0
	global_load_dwordx4 v[52:55], v[52:53], off offset:1792
	s_nop 0
	global_load_dwordx4 v[56:59], v[56:57], off
	s_nop 0
	global_load_dwordx4 v[60:63], v[60:61], off offset:1792
	v_lshlrev_b32_e32 v66, 4, v66
	v_mul_lo_u32 v67, v69, s64
	v_and_b32_e32 v66, 0x70, v66
	v_readlane_b32 s0, v254, 20
	v_add3_u32 v70, 0, v67, v66
	v_mov_b32_e32 v67, v192
	v_readlane_b32 s1, v254, 21
	v_readlane_b32 s5, v251, 23
	v_lshlrev_b32_e32 v72, 1, v68
	v_lshl_add_u64 v[66:67], s[0:1], 0, v[66:67]
	v_mul_u32_u24_e32 v71, 0x90, v71
	v_readlane_b32 s0, v251, 20
	v_add3_u32 v71, 0, v72, v71
	s_mov_b32 s4, s0
	s_mov_b32 s5, s75
	v_readlane_b32 s6, v251, 24
	v_readlane_b32 s7, v251, 25
	v_readlane_b32 s8, v251, 26
	v_readlane_b32 s9, v251, 27
	v_readlane_b32 s10, v251, 28
	v_readlane_b32 s11, v251, 29
	v_readlane_b32 s12, v251, 30
	v_readlane_b32 s13, v251, 31
	v_readlane_b32 s14, v251, 32
	v_readlane_b32 s15, v251, 33
	v_readlane_b32 s16, v251, 34
	v_readlane_b32 s17, v251, 35
	v_readlane_b32 s1, v251, 21
	v_lshrrev_b32_e32 v87, 4, v230
	v_and_b32_e32 v88, 3, v230
	v_lshlrev_b32_e32 v88, 3, v88
	v_xor_b32_e32 v88, v87, v88
	v_sub_u32_e32 v88, v88, v87
	v_bfe_u32 v87, v230, 2, 1
	v_lshlrev_b32_e32 v87, 6, v87
	v_lshl_add_u32 v86, v88, 1, v71
	v_add_u32_e32 v71, v86, v87
	v_sub_u32_e32 v86, v86, v87
	v_and_b32_e32 v87, 7, v230
	v_bfe_u32 v88, v230, 5, 3
	v_xor_b32_e32 v88, v87, v88
	v_sub_u32_e32 v88, v88, v87
	v_lshl_add_u32 v70, v88, 4, v70
	s_branch .LBB0_50

; __device__ __forceinline__ bf16_t f2bf(float f) { unsigned u = __float_as_uint(f); u += 0x7FFFu + ((u >> 16) & 1u); return (bf16_t)(u >> 16); }
; __device__ __forceinline__ void convert_wt(LAS unsigned char* lds, const float* __restrict__ W, bf16_t* __restrict__ Wt, int K, int N, int mode) {
;     ...
;     for (; st < nsuper; st += gridDim.x) {
;         const int k0 = (st / nsn) * 64, n0 = (st % nsn) * 512;
; #pragma unroll
;         for (int s_ = 0; s_ < 8; ++s_)
; #pragma unroll
;             for (int i_ = 0; i_ < 2; ++i_)
; #pragma unroll
;                 for (int e = 0; e < 4; ++e) T[s_ * 4608 + (c4 + e) * 72 + kk0 + 32 * i_] = f2bf(v[s_ * 2 + i_][e]);
;         __syncthreads();
;         const int nx = st + gridDim.x;
;         if (nx < nsuper) CW_LOAD(nx);
.LBB0_50:
	s_waitcnt vmcnt(15)
	v_bfe_u32 v72, v0, 16, 1
	v_add3_u32 v72, v0, v72, s70
	ds_write_b16_d16_hi v71, v72
	v_bfe_u32 v72, v1, 16, 1
	v_add3_u32 v72, v1, v72, s70
	ds_write_b16_d16_hi v71, v72 offset:144
	v_bfe_u32 v72, v2, 16, 1
	v_add3_u32 v72, v2, v72, s70
	ds_write_b16_d16_hi v71, v72 offset:288
	v_bfe_u32 v72, v3, 16, 1
	v_add3_u32 v72, v3, v72, s70
	ds_write_b16_d16_hi v71, v72 offset:432
	s_waitcnt vmcnt(1)
	v_bfe_u32 v72, v56, 16, 1
	v_add3_u32 v72, v56, v72, s70
	ds_write_b16_d16_hi v86, v72 offset:64
	v_bfe_u32 v72, v57, 16, 1
	v_add3_u32 v72, v57, v72, s70
	ds_write_b16_d16_hi v86, v72 offset:208
	v_bfe_u32 v72, v58, 16, 1
	v_add3_u32 v72, v58, v72, s70
	ds_write_b16_d16_hi v86, v72 offset:352
	v_bfe_u32 v72, v59, 16, 1
	v_add3_u32 v72, v59, v72, s70
	ds_write_b16_d16_hi v86, v72 offset:496
	v_bfe_u32 v72, v4, 16, 1
	v_add3_u32 v72, v4, v72, s70
	ds_write_b16_d16_hi v71, v72 offset:9216
	v_bfe_u32 v72, v5, 16, 1
	v_add3_u32 v72, v5, v72, s70
	ds_write_b16_d16_hi v71, v72 offset:9360
	v_bfe_u32 v72, v6, 16, 1
	v_add3_u32 v72, v6, v72, s70
	ds_write_b16_d16_hi v71, v72 offset:9504
	v_bfe_u32 v72, v7, 16, 1
	v_add3_u32 v72, v7, v72, s70
	ds_write_b16_d16_hi v71, v72 offset:9648
	v_bfe_u32 v72, v8, 16, 1
	v_add3_u32 v72, v8, v72, s70
	ds_write_b16_d16_hi v86, v72 offset:9280
	v_bfe_u32 v72, v9, 16, 1
	v_add3_u32 v72, v9, v72, s70
	ds_write_b16_d16_hi v86, v72 offset:9424
	v_bfe_u32 v72, v10, 16, 1
	v_add3_u32 v72, v10, v72, s70
	ds_write_b16_d16_hi v86, v72 offset:9568
	v_bfe_u32 v72, v11, 16, 1
	v_add3_u32 v72, v11, v72, s70
	ds_write_b16_d16_hi v86, v72 offset:9712
	v_bfe_u32 v72, v16, 16, 1
	v_add3_u32 v72, v16, v72, s70
	ds_write_b16_d16_hi v71, v72 offset:18432
	v_bfe_u32 v72, v17, 16, 1
	v_add3_u32 v72, v17, v72, s70
	ds_write_b16_d16_hi v71, v72 offset:18576
	v_bfe_u32 v72, v18, 16, 1
	v_add3_u32 v72, v18, v72, s70
	ds_write_b16_d16_hi v71, v72 offset:18720
	v_bfe_u32 v72, v19, 16, 1
	v_add3_u32 v72, v19, v72, s70
	ds_write_b16_d16_hi v71, v72 offset:18864
	v_bfe_u32 v72, v12, 16, 1
	v_add3_u32 v72, v12, v72, s70
	ds_write_b16_d16_hi v86, v72 offset:18496
	v_bfe_u32 v72, v13, 16, 1
	v_add3_u32 v72, v13, v72, s70
	ds_write_b16_d16_hi v86, v72 offset:18640
	v_bfe_u32 v72, v14, 16, 1
	v_add3_u32 v72, v14, v72, s70
	ds_write_b16_d16_hi v86, v72 offset:18784
	v_bfe_u32 v72, v15, 16, 1
	v_add3_u32 v72, v15, v72, s70
	ds_write_b16_d16_hi v86, v72 offset:18928
	v_bfe_u32 v72, v20, 16, 1
	v_add3_u32 v72, v20, v72, s70
	ds_write_b16_d16_hi v71, v72 offset:27648
	v_bfe_u32 v72, v21, 16, 1
	v_add3_u32 v72, v21, v72, s70
	ds_write_b16_d16_hi v71, v72 offset:27792
	v_bfe_u32 v72, v22, 16, 1
	v_add3_u32 v72, v22, v72, s70
	ds_write_b16_d16_hi v71, v72 offset:27936
	v_bfe_u32 v72, v23, 16, 1
	v_add3_u32 v72, v23, v72, s70
	ds_write_b16_d16_hi v71, v72 offset:28080
	v_bfe_u32 v72, v24, 16, 1
	v_add3_u32 v72, v24, v72, s70
	ds_write_b16_d16_hi v86, v72 offset:27712
	v_bfe_u32 v72, v25, 16, 1
	v_add3_u32 v72, v25, v72, s70
	ds_write_b16_d16_hi v86, v72 offset:27856
	v_bfe_u32 v72, v26, 16, 1
	v_add3_u32 v72, v26, v72, s70
	ds_write_b16_d16_hi v86, v72 offset:28000
	v_bfe_u32 v72, v27, 16, 1
	v_add3_u32 v72, v27, v72, s70
	ds_write_b16_d16_hi v86, v72 offset:28144
	v_bfe_u32 v72, v32, 16, 1
	v_add3_u32 v72, v32, v72, s70
	ds_write_b16_d16_hi v71, v72 offset:36864
	v_bfe_u32 v72, v33, 16, 1
	v_add3_u32 v72, v33, v72, s70
	ds_write_b16_d16_hi v71, v72 offset:37008
	v_bfe_u32 v72, v34, 16, 1
	v_add3_u32 v72, v34, v72, s70
	ds_write_b16_d16_hi v71, v72 offset:37152
	v_bfe_u32 v72, v35, 16, 1
	v_add3_u32 v72, v35, v72, s70
	ds_write_b16_d16_hi v71, v72 offset:37296
	v_bfe_u32 v72, v28, 16, 1
	v_add3_u32 v72, v28, v72, s70
	ds_write_b16_d16_hi v86, v72 offset:36928
	v_bfe_u32 v72, v29, 16, 1
	v_add3_u32 v72, v29, v72, s70
	ds_write_b16_d16_hi v86, v72 offset:37072
	v_bfe_u32 v72, v30, 16, 1
	v_add3_u32 v72, v30, v72, s70
	ds_write_b16_d16_hi v86, v72 offset:37216
	v_bfe_u32 v72, v31, 16, 1
	v_add3_u32 v72, v31, v72, s70
	ds_write_b16_d16_hi v86, v72 offset:37360
	v_bfe_u32 v72, v36, 16, 1
	v_add3_u32 v72, v36, v72, s70
	ds_write_b16_d16_hi v71, v72 offset:46080
	v_bfe_u32 v72, v37, 16, 1
	v_add3_u32 v72, v37, v72, s70
	ds_write_b16_d16_hi v71, v72 offset:46224
	v_bfe_u32 v72, v38, 16, 1
	v_add3_u32 v72, v38, v72, s70
	ds_write_b16_d16_hi v71, v72 offset:46368
	v_bfe_u32 v72, v39, 16, 1
	v_add3_u32 v72, v39, v72, s70
	ds_write_b16_d16_hi v71, v72 offset:46512
	v_bfe_u32 v72, v40, 16, 1
	v_add3_u32 v72, v40, v72, s70
	ds_write_b16_d16_hi v86, v72 offset:46144
	v_bfe_u32 v72, v41, 16, 1
	v_add3_u32 v72, v41, v72, s70
	ds_write_b16_d16_hi v86, v72 offset:46288
	v_bfe_u32 v72, v42, 16, 1
	v_add3_u32 v72, v42, v72, s70
	ds_write_b16_d16_hi v86, v72 offset:46432
	v_bfe_u32 v72, v43, 16, 1
	v_add3_u32 v72, v43, v72, s70
	ds_write_b16_d16_hi v86, v72 offset:46576
	v_bfe_u32 v72, v48, 16, 1
	v_add3_u32 v72, v48, v72, s70
	ds_write_b16_d16_hi v71, v72 offset:55296
	v_bfe_u32 v72, v49, 16, 1
	v_add3_u32 v72, v49, v72, s70
	ds_write_b16_d16_hi v71, v72 offset:55440
	v_bfe_u32 v72, v50, 16, 1
	v_add3_u32 v72, v50, v72, s70
	ds_write_b16_d16_hi v71, v72 offset:55584
	v_bfe_u32 v72, v51, 16, 1
	v_add3_u32 v72, v51, v72, s70
	ds_write_b16_d16_hi v71, v72 offset:55728
	v_bfe_u32 v72, v44, 16, 1
	v_add3_u32 v72, v44, v72, s70
	ds_write_b16_d16_hi v86, v72 offset:55360
	v_bfe_u32 v72, v45, 16, 1
	v_add3_u32 v72, v45, v72, s70
	ds_write_b16_d16_hi v86, v72 offset:55504
	v_bfe_u32 v72, v46, 16, 1
	v_add3_u32 v72, v46, v72, s70
	ds_write_b16_d16_hi v86, v72 offset:55648
	v_bfe_u32 v72, v47, 16, 1
	v_add3_u32 v72, v47, v72, s70
	ds_write_b16_d16_hi v86, v72 offset:55792
	v_bfe_u32 v72, v52, 16, 1
	v_add3_u32 v72, v52, v72, s70
	ds_write_b16_d16_hi v71, v72 offset:64512
	v_bfe_u32 v72, v53, 16, 1
	v_add3_u32 v72, v53, v72, s70
	ds_write_b16_d16_hi v71, v72 offset:64656
	v_bfe_u32 v72, v54, 16, 1
	v_add3_u32 v72, v54, v72, s70
	ds_write_b16_d16_hi v71, v72 offset:64800
	v_bfe_u32 v72, v55, 16, 1
	v_add3_u32 v72, v55, v72, s70
	ds_write_b16_d16_hi v71, v72 offset:64944
	s_waitcnt vmcnt(0)
	v_bfe_u32 v72, v60, 16, 1
	v_add3_u32 v72, v60, v72, s70
	ds_write_b16_d16_hi v86, v72 offset:64576
	v_bfe_u32 v72, v61, 16, 1
	v_add3_u32 v72, v61, v72, s70
	ds_write_b16_d16_hi v86, v72 offset:64720
	v_bfe_u32 v72, v62, 16, 1
	s_add_i32 s6, s5, s80
	v_add3_u32 v72, v62, v72, s70
	s_cmpk_gt_i32 s6, 0x7f
	ds_write_b16_d16_hi v86, v72 offset:64864
	v_bfe_u32 v72, v63, 16, 1
	s_cselect_b64 s[0:1], -1, 0
	v_add3_u32 v72, v63, v72, s70
	s_and_b64 vcc, exec, s[0:1]
	ds_write_b16_d16_hi v86, v72 offset:65008
	s_waitcnt lgkmcnt(0)
	s_barrier
; __device__ __forceinline__ void convert_wt(LAS unsigned char* lds, const float* __restrict__ W, bf16_t* __restrict__ Wt, int K, int N, int mode) {
;     ...
;         const int nx = st + gridDim.x;
;         if (nx < nsuper) CW_LOAD(nx);
	s_cbranch_vccnz .LBB0_49
	s_ashr_i32 s7, s6, 31
	s_lshr_b32 s7, s7, 30
	s_add_i32 s7, s6, s7
	s_ashr_i32 s7, s7, 2
	v_readlane_b32 s8, v250, 20
	s_add_i32 s8, s8, s4
	s_lshl_b32 s9, s7, 11
	s_sub_i32 s8, s8, s9
	v_lshl_add_u32 v0, s7, 6, v68
	v_ashrrev_i32_e32 v1, 31, v0
	s_ashr_i32 s9, s8, 31
	v_lshl_add_u64 v[2:3], s[8:9], 2, v[64:65]
	v_lshlrev_b64 v[0:1], 13, v[0:1]
	v_lshl_add_u64 v[52:53], v[2:3], 0, v[0:1]
	s_mov_b64 s[8:9], 0x40000
	v_add_co_u32_e32 v56, vcc, s71, v52
	v_lshl_add_u64 v[60:61], v[52:53], 0, s[8:9]
	s_nop 0
	v_addc_co_u32_e32 v57, vcc, 0, v53, vcc
	global_load_dwordx4 v[0:3], v[52:53], off
	global_load_dwordx4 v[4:7], v[52:53], off offset:256
	global_load_dwordx4 v[8:11], v[60:61], off offset:256
	global_load_dwordx4 v[12:15], v[60:61], off offset:512
	global_load_dwordx4 v[16:19], v[52:53], off offset:512
	global_load_dwordx4 v[20:23], v[52:53], off offset:768
	global_load_dwordx4 v[24:27], v[60:61], off offset:768
	global_load_dwordx4 v[28:31], v[60:61], off offset:1024
	global_load_dwordx4 v[32:35], v[52:53], off offset:1024
	global_load_dwordx4 v[36:39], v[52:53], off offset:1280
	global_load_dwordx4 v[40:43], v[60:61], off offset:1280
	global_load_dwordx4 v[44:47], v[60:61], off offset:1536
	global_load_dwordx4 v[48:51], v[52:53], off offset:1536
	s_nop 0
	global_load_dwordx4 v[52:55], v[52:53], off offset:1792
	s_nop 0
	global_load_dwordx4 v[56:59], v[56:57], off
	s_nop 0
	global_load_dwordx4 v[60:63], v[60:61], off offset:1792
	s_branch .LBB0_49
